# peel first K-tile of every GEMM unit (MFMA srcC=0, no accumulator zeroing v_movs) + epilogue-start vmcnt(0)->vmcnt(8) in w_in/GU
# speedup vs baseline: 1.0111x; 1.0064x over previous
.LBB0_162:
	s_ashr_i32 s29, s28, 31
	s_lshl_b64 s[30:31], s[28:29], 19
	s_add_u32 s30, s62, s30
	s_addc_u32 s31, s63, s31
	s_and_b64 s[34:35], s[36:37], exec
	s_cselect_b32 s29, s31, s43
	s_cselect_b32 s60, s30, s42
	s_ashr_i32 s27, s26, 31
	s_lshl_b64 s[34:35], s[26:27], 19
	s_add_u32 s34, s17, s34
	s_addc_u32 s35, s18, s35
	s_and_b64 s[44:45], s[36:37], exec
	s_cselect_b32 s27, s35, s41
	s_cselect_b32 s61, s34, s40
	s_lshl_b32 s3, s38, 8
	v_add_u32_e32 v0, s3, v141
	s_add_u32 s64, s40, 0x100
	v_ashrrev_i32_e32 v1, 31, v0
	s_addc_u32 s65, s41, 0
	v_lshl_add_u64 v[156:157], v[0:1], 2, s[72:73]
	s_add_u32 s38, s42, 0xa000
	v_mov_b32_e32 v0, 0
	s_addc_u32 s39, s43, 0
	s_mov_b32 s66, -2
	s_mov_b64 s[40:41], 0
	s_add_u32 s42, s38, 0x6000
	s_addc_u32 s43, s39, 0
	s_and_b64 s[40:41], s[40:41], exec
	s_cselect_b32 s44, s60, s42
	s_cselect_b32 s45, s29, s43
	s_cselect_b32 s43, s27, s65
	s_cselect_b32 s42, s61, s64
	s_add_u32 s40, s44, 0x8000
	s_addc_u32 s41, s45, 0
	s_add_i32 s67, 0, 0x10000
	v_add_u32_e32 v159, s67, v143
	s_add_i32 s70, 0, 0x14000
	ds_read_b128 v[160:163], v159
	ds_read_b128 v[164:167], v159 offset:1024
	ds_read_b128 v[168:171], v159 offset:2048
	ds_read_b128 v[172:175], v159 offset:3072
	v_add_u32_e32 v159, s70, v143
	ds_read_b128 v[176:179], v159
	ds_read_b128 v[180:183], v159 offset:1024
	ds_read_b128 v[184:187], v159 offset:2048
	ds_read_b128 v[188:191], v159 offset:3072
	v_lshl_add_u64 v[214:215], s[38:39], 0, v[136:137]
	s_add_i32 m0, s46, 0xc000
	ds_read_b128 v[192:195], v153
	ds_read_b128 v[196:199], v153 offset:1024
	ds_read_b128 v[200:203], v153 offset:2048
	ds_read_b128 v[204:207], v153 offset:3072
	ds_read_b128 v[218:221], v153 offset:4096
	ds_read_b128 v[222:225], v153 offset:5120
	ds_read_b128 v[226:229], v153 offset:6144
	ds_read_b128 v[230:233], v153 offset:7168
	global_load_lds_dwordx4 v[214:215], off
	v_lshl_add_u64 v[214:215], s[38:39], 0, v[138:139]
	s_add_i32 m0, s46, 0xe000
	s_nop 0
	global_load_lds_dwordx4 v[214:215], off
	s_waitcnt vmcnt(8)
	s_waitcnt lgkmcnt(0)
	s_barrier
	s_setprio 1
	s_waitcnt lgkmcnt(0)
	v_mfma_f32_16x16x32_bf16 v[124:127], v[160:163], v[192:195], 0
	v_mfma_f32_16x16x32_bf16 v[120:123], v[168:171], v[192:195], 0
	v_mfma_f32_16x16x32_bf16 v[108:111], v[160:163], v[200:203], 0
	v_mfma_f32_16x16x32_bf16 v[104:107], v[168:171], v[200:203], 0
	v_mfma_f32_16x16x32_bf16 v[92:95], v[160:163], v[218:221], 0
	v_mfma_f32_16x16x32_bf16 v[88:91], v[168:171], v[218:221], 0
	v_mfma_f32_16x16x32_bf16 v[76:79], v[160:163], v[226:229], 0
	v_mfma_f32_16x16x32_bf16 v[72:75], v[168:171], v[226:229], 0
	v_mfma_f32_16x16x32_bf16 v[124:127], v[164:167], v[196:199], v[124:127]
	v_mfma_f32_16x16x32_bf16 v[120:123], v[172:175], v[196:199], v[120:123]
	v_mfma_f32_16x16x32_bf16 v[108:111], v[164:167], v[204:207], v[108:111]
	v_mfma_f32_16x16x32_bf16 v[104:107], v[172:175], v[204:207], v[104:107]
	v_mfma_f32_16x16x32_bf16 v[92:95], v[164:167], v[222:225], v[92:95]
	v_mfma_f32_16x16x32_bf16 v[88:91], v[172:175], v[222:225], v[88:91]
	v_mfma_f32_16x16x32_bf16 v[76:79], v[164:167], v[230:233], v[76:79]
	v_mfma_f32_16x16x32_bf16 v[72:75], v[172:175], v[230:233], v[72:75]
	s_setprio 0
	s_setprio 1
	v_mfma_f32_16x16x32_bf16 v[116:119], v[176:179], v[192:195], 0
	v_mfma_f32_16x16x32_bf16 v[112:115], v[184:187], v[192:195], 0
	v_mfma_f32_16x16x32_bf16 v[100:103], v[176:179], v[200:203], 0
	v_mfma_f32_16x16x32_bf16 v[96:99], v[184:187], v[200:203], 0
	v_mfma_f32_16x16x32_bf16 v[84:87], v[176:179], v[218:221], 0
	v_mfma_f32_16x16x32_bf16 v[80:83], v[184:187], v[218:221], 0
	v_mfma_f32_16x16x32_bf16 v[68:71], v[176:179], v[226:229], 0
	v_mfma_f32_16x16x32_bf16 v[64:67], v[184:187], v[226:229], 0
	v_mfma_f32_16x16x32_bf16 v[116:119], v[180:183], v[196:199], v[116:119]
	v_mfma_f32_16x16x32_bf16 v[112:115], v[188:191], v[196:199], v[112:115]
	v_mfma_f32_16x16x32_bf16 v[100:103], v[180:183], v[204:207], v[100:103]
	v_mfma_f32_16x16x32_bf16 v[96:99], v[188:191], v[204:207], v[96:99]
	v_mfma_f32_16x16x32_bf16 v[84:87], v[180:183], v[222:225], v[84:87]
	v_mfma_f32_16x16x32_bf16 v[80:83], v[188:191], v[222:225], v[80:83]
	v_mfma_f32_16x16x32_bf16 v[68:71], v[180:183], v[230:233], v[68:71]
	v_mfma_f32_16x16x32_bf16 v[64:67], v[188:191], v[230:233], v[64:67]
	s_setprio 0
	s_barrier
	s_add_i32 s67, s67, s19
	v_lshl_add_u64 v[214:215], s[42:43], 0, v[132:133]
	s_mov_b32 m0, s67
	ds_read_b128 v[192:195], v153 offset:16384
	ds_read_b128 v[196:199], v153 offset:17408
	ds_read_b128 v[200:203], v153 offset:18432
	ds_read_b128 v[204:207], v153 offset:19456
	ds_read_b128 v[218:221], v153 offset:20480
	ds_read_b128 v[222:225], v153 offset:21504
	ds_read_b128 v[226:229], v153 offset:22528
	ds_read_b128 v[230:233], v153 offset:23552
	global_load_lds_dwordx4 v[214:215], off
	s_add_i32 m0, s67, 0x2000
	s_add_u32 s68, s42, 0x10000
	v_lshl_add_u64 v[216:217], s[42:43], 0, v[128:129]
	s_addc_u32 s69, s43, 0
	s_add_i32 s67, s70, s19
	global_load_lds_dwordx4 v[216:217], off
	v_lshl_add_u64 v[234:235], s[68:69], 0, v[132:133]
	s_mov_b32 m0, s67
	s_nop 0
	global_load_lds_dwordx4 v[234:235], off
	v_lshl_add_u64 v[234:235], s[68:69], 0, v[128:129]
	s_add_i32 m0, s67, 0x2000
	s_nop 0
	global_load_lds_dwordx4 v[234:235], off
	v_lshl_add_u64 v[234:235], s[44:45], 0, v[134:135]
	s_mov_b32 m0, s46
	s_nop 0
	global_load_lds_dwordx4 v[234:235], off
	v_lshl_add_u64 v[234:235], s[44:45], 0, v[130:131]
	s_mov_b32 m0, s47
	s_nop 0
	global_load_lds_dwordx4 v[234:235], off
	s_waitcnt vmcnt(8)
	s_waitcnt lgkmcnt(0)
	s_barrier
	s_setprio 1
	s_waitcnt lgkmcnt(0)
	v_mfma_f32_16x16x32_bf16 v[60:63], v[160:163], v[192:195], 0
	v_mfma_f32_16x16x32_bf16 v[56:59], v[168:171], v[192:195], 0
	v_mfma_f32_16x16x32_bf16 v[44:47], v[160:163], v[200:203], 0
	v_mfma_f32_16x16x32_bf16 v[40:43], v[168:171], v[200:203], 0
	v_mfma_f32_16x16x32_bf16 v[28:31], v[160:163], v[218:221], 0
	v_mfma_f32_16x16x32_bf16 v[24:27], v[168:171], v[218:221], 0
	v_mfma_f32_16x16x32_bf16 v[12:15], v[160:163], v[226:229], 0
	v_mfma_f32_16x16x32_bf16 v[8:11], v[168:171], v[226:229], 0
	v_mfma_f32_16x16x32_bf16 v[60:63], v[164:167], v[196:199], v[60:63]
	v_mfma_f32_16x16x32_bf16 v[56:59], v[172:175], v[196:199], v[56:59]
	v_mfma_f32_16x16x32_bf16 v[44:47], v[164:167], v[204:207], v[44:47]
	v_mfma_f32_16x16x32_bf16 v[40:43], v[172:175], v[204:207], v[40:43]
	v_mfma_f32_16x16x32_bf16 v[28:31], v[164:167], v[222:225], v[28:31]
	v_mfma_f32_16x16x32_bf16 v[24:27], v[172:175], v[222:225], v[24:27]
	v_mfma_f32_16x16x32_bf16 v[12:15], v[164:167], v[230:233], v[12:15]
	v_mfma_f32_16x16x32_bf16 v[8:11], v[172:175], v[230:233], v[8:11]
	s_setprio 0
	s_setprio 1
	v_mfma_f32_16x16x32_bf16 v[52:55], v[176:179], v[192:195], 0
	v_mfma_f32_16x16x32_bf16 v[48:51], v[184:187], v[192:195], 0
	v_mfma_f32_16x16x32_bf16 v[36:39], v[176:179], v[200:203], 0
	v_mfma_f32_16x16x32_bf16 v[32:35], v[184:187], v[200:203], 0
	v_mfma_f32_16x16x32_bf16 v[20:23], v[176:179], v[218:221], 0
	v_mfma_f32_16x16x32_bf16 v[16:19], v[184:187], v[218:221], 0
	v_mfma_f32_16x16x32_bf16 v[4:7], v[176:179], v[226:229], 0
	v_mfma_f32_16x16x32_bf16 v[0:3], v[184:187], v[226:229], 0
	v_mfma_f32_16x16x32_bf16 v[52:55], v[180:183], v[196:199], v[52:55]
	v_mfma_f32_16x16x32_bf16 v[48:51], v[188:191], v[196:199], v[48:51]
	v_mfma_f32_16x16x32_bf16 v[36:39], v[180:183], v[204:207], v[36:39]
	v_mfma_f32_16x16x32_bf16 v[32:35], v[188:191], v[204:207], v[32:35]
	v_mfma_f32_16x16x32_bf16 v[20:23], v[180:183], v[222:225], v[20:23]
	v_mfma_f32_16x16x32_bf16 v[16:19], v[188:191], v[222:225], v[16:19]
	v_mfma_f32_16x16x32_bf16 v[4:7], v[180:183], v[230:233], v[4:7]
	v_mfma_f32_16x16x32_bf16 v[0:3], v[188:191], v[230:233], v[0:3]
	s_setprio 0
	s_barrier
	s_branch .Lwin_mid

.Lwin_mid:
	s_add_i32 s67, 0, 0x18000
	v_add_u32_e32 v159, s67, v143
	s_add_i32 s68, 0, 0x1c000
	ds_read_b128 v[160:163], v159
	ds_read_b128 v[164:167], v159 offset:1024
	ds_read_b128 v[168:171], v159 offset:2048
	ds_read_b128 v[172:175], v159 offset:3072
	v_add_u32_e32 v159, s68, v143
	ds_read_b128 v[176:179], v159
	ds_read_b128 v[180:183], v159 offset:1024
	ds_read_b128 v[184:187], v159 offset:2048
	ds_read_b128 v[188:191], v159 offset:3072
	s_add_u32 s44, s44, 0x2000
	s_addc_u32 s45, s45, 0
	s_mov_b32 m0, s48
	v_lshl_add_u64 v[234:235], s[44:45], 0, v[134:135]
	ds_read_b128 v[192:195], v153 offset:32768
	ds_read_b128 v[196:199], v153 offset:33792
	ds_read_b128 v[200:203], v153 offset:34816
	ds_read_b128 v[204:207], v153 offset:35840
	ds_read_b128 v[218:221], v153 offset:36864
	ds_read_b128 v[222:225], v153 offset:37888
	ds_read_b128 v[226:229], v153 offset:38912
	ds_read_b128 v[230:233], v153 offset:39936
	global_load_lds_dwordx4 v[234:235], off
	v_lshl_add_u64 v[234:235], s[44:45], 0, v[130:131]
	s_mov_b32 m0, s49
	s_nop 0
	global_load_lds_dwordx4 v[234:235], off
	s_waitcnt vmcnt(8)
	s_waitcnt lgkmcnt(0)
	s_barrier
	s_setprio 1
	s_waitcnt lgkmcnt(0)
	v_mfma_f32_16x16x32_bf16 v[124:127], v[160:163], v[192:195], v[124:127]
	v_mfma_f32_16x16x32_bf16 v[120:123], v[168:171], v[192:195], v[120:123]
	v_mfma_f32_16x16x32_bf16 v[108:111], v[160:163], v[200:203], v[108:111]
	v_mfma_f32_16x16x32_bf16 v[104:107], v[168:171], v[200:203], v[104:107]
	v_mfma_f32_16x16x32_bf16 v[92:95], v[160:163], v[218:221], v[92:95]
	v_mfma_f32_16x16x32_bf16 v[88:91], v[168:171], v[218:221], v[88:91]
	v_mfma_f32_16x16x32_bf16 v[76:79], v[160:163], v[226:229], v[76:79]
	v_mfma_f32_16x16x32_bf16 v[72:75], v[168:171], v[226:229], v[72:75]
	v_mfma_f32_16x16x32_bf16 v[124:127], v[164:167], v[196:199], v[124:127]
	v_mfma_f32_16x16x32_bf16 v[120:123], v[172:175], v[196:199], v[120:123]
	v_mfma_f32_16x16x32_bf16 v[108:111], v[164:167], v[204:207], v[108:111]
	v_mfma_f32_16x16x32_bf16 v[104:107], v[172:175], v[204:207], v[104:107]
	v_mfma_f32_16x16x32_bf16 v[92:95], v[164:167], v[222:225], v[92:95]
	v_mfma_f32_16x16x32_bf16 v[88:91], v[172:175], v[222:225], v[88:91]
	v_mfma_f32_16x16x32_bf16 v[76:79], v[164:167], v[230:233], v[76:79]
	v_mfma_f32_16x16x32_bf16 v[72:75], v[172:175], v[230:233], v[72:75]
	s_setprio 0
	s_setprio 1
	v_mfma_f32_16x16x32_bf16 v[116:119], v[176:179], v[192:195], v[116:119]
	v_mfma_f32_16x16x32_bf16 v[112:115], v[184:187], v[192:195], v[112:115]
	v_mfma_f32_16x16x32_bf16 v[100:103], v[176:179], v[200:203], v[100:103]
	v_mfma_f32_16x16x32_bf16 v[96:99], v[184:187], v[200:203], v[96:99]
	v_mfma_f32_16x16x32_bf16 v[84:87], v[176:179], v[218:221], v[84:87]
	v_mfma_f32_16x16x32_bf16 v[80:83], v[184:187], v[218:221], v[80:83]
	v_mfma_f32_16x16x32_bf16 v[68:71], v[176:179], v[226:229], v[68:71]
	v_mfma_f32_16x16x32_bf16 v[64:67], v[184:187], v[226:229], v[64:67]
	v_mfma_f32_16x16x32_bf16 v[116:119], v[180:183], v[196:199], v[116:119]
	v_mfma_f32_16x16x32_bf16 v[112:115], v[188:191], v[196:199], v[112:115]
	v_mfma_f32_16x16x32_bf16 v[100:103], v[180:183], v[204:207], v[100:103]
	v_mfma_f32_16x16x32_bf16 v[96:99], v[188:191], v[204:207], v[96:99]
	v_mfma_f32_16x16x32_bf16 v[84:87], v[180:183], v[222:225], v[84:87]
	v_mfma_f32_16x16x32_bf16 v[80:83], v[188:191], v[222:225], v[80:83]
	v_mfma_f32_16x16x32_bf16 v[68:71], v[180:183], v[230:233], v[68:71]
	v_mfma_f32_16x16x32_bf16 v[64:67], v[188:191], v[230:233], v[64:67]
	s_setprio 0
	s_barrier
	s_add_i32 s44, s67, s19
	v_lshl_add_u64 v[214:215], v[214:215], 0, s[4:5]
	s_mov_b32 m0, s44
	ds_read_b128 v[192:195], v153 offset:49152
	ds_read_b128 v[196:199], v153 offset:50176
	ds_read_b128 v[200:203], v153 offset:51200
	ds_read_b128 v[204:207], v153 offset:52224
	ds_read_b128 v[218:221], v153 offset:53248
	ds_read_b128 v[222:225], v153 offset:54272
	ds_read_b128 v[226:229], v153 offset:55296
	ds_read_b128 v[230:233], v153 offset:56320
	global_load_lds_dwordx4 v[214:215], off
	s_add_i32 m0, s44, 0x2000
	s_add_u32 s42, s42, 0x10080
	v_lshl_add_u64 v[214:215], v[216:217], 0, s[4:5]
	s_addc_u32 s43, s43, 0
	s_add_i32 s44, s68, s19
	global_load_lds_dwordx4 v[214:215], off
	v_lshl_add_u64 v[214:215], s[42:43], 0, v[132:133]
	s_mov_b32 m0, s44
	s_nop 0
	global_load_lds_dwordx4 v[214:215], off
	v_lshl_add_u64 v[214:215], s[42:43], 0, v[128:129]
	s_add_i32 m0, s44, 0x2000
	s_nop 0
	global_load_lds_dwordx4 v[214:215], off
	v_lshl_add_u64 v[214:215], s[40:41], 0, v[134:135]
	s_mov_b32 m0, s52
	s_nop 0
	global_load_lds_dwordx4 v[214:215], off
	v_lshl_add_u64 v[214:215], s[40:41], 0, v[130:131]
	s_mov_b32 m0, s53
	s_nop 0
	global_load_lds_dwordx4 v[214:215], off
	s_waitcnt vmcnt(8)
	s_waitcnt lgkmcnt(0)
	s_barrier
	s_setprio 1
	s_waitcnt lgkmcnt(0)
	v_mfma_f32_16x16x32_bf16 v[60:63], v[160:163], v[192:195], v[60:63]
	v_mfma_f32_16x16x32_bf16 v[56:59], v[168:171], v[192:195], v[56:59]
	v_mfma_f32_16x16x32_bf16 v[44:47], v[160:163], v[200:203], v[44:47]
	v_mfma_f32_16x16x32_bf16 v[40:43], v[168:171], v[200:203], v[40:43]
	v_mfma_f32_16x16x32_bf16 v[28:31], v[160:163], v[218:221], v[28:31]
	v_mfma_f32_16x16x32_bf16 v[24:27], v[168:171], v[218:221], v[24:27]
	v_mfma_f32_16x16x32_bf16 v[12:15], v[160:163], v[226:229], v[12:15]
	v_mfma_f32_16x16x32_bf16 v[8:11], v[168:171], v[226:229], v[8:11]
	v_mfma_f32_16x16x32_bf16 v[60:63], v[164:167], v[196:199], v[60:63]
	v_mfma_f32_16x16x32_bf16 v[56:59], v[172:175], v[196:199], v[56:59]
	v_mfma_f32_16x16x32_bf16 v[44:47], v[164:167], v[204:207], v[44:47]
	v_mfma_f32_16x16x32_bf16 v[40:43], v[172:175], v[204:207], v[40:43]
	v_mfma_f32_16x16x32_bf16 v[28:31], v[164:167], v[222:225], v[28:31]
	v_mfma_f32_16x16x32_bf16 v[24:27], v[172:175], v[222:225], v[24:27]
	v_mfma_f32_16x16x32_bf16 v[12:15], v[164:167], v[230:233], v[12:15]
	v_mfma_f32_16x16x32_bf16 v[8:11], v[172:175], v[230:233], v[8:11]
	s_setprio 0
	s_setprio 1
	v_mfma_f32_16x16x32_bf16 v[52:55], v[176:179], v[192:195], v[52:55]
	v_mfma_f32_16x16x32_bf16 v[48:51], v[184:187], v[192:195], v[48:51]
	v_mfma_f32_16x16x32_bf16 v[36:39], v[176:179], v[200:203], v[36:39]
	v_mfma_f32_16x16x32_bf16 v[32:35], v[184:187], v[200:203], v[32:35]
	v_mfma_f32_16x16x32_bf16 v[20:23], v[176:179], v[218:221], v[20:23]
	v_mfma_f32_16x16x32_bf16 v[16:19], v[184:187], v[218:221], v[16:19]
	v_mfma_f32_16x16x32_bf16 v[4:7], v[176:179], v[226:229], v[4:7]
	v_mfma_f32_16x16x32_bf16 v[0:3], v[184:187], v[226:229], v[0:3]
	v_mfma_f32_16x16x32_bf16 v[52:55], v[180:183], v[196:199], v[52:55]
	v_mfma_f32_16x16x32_bf16 v[48:51], v[188:191], v[196:199], v[48:51]
	v_mfma_f32_16x16x32_bf16 v[36:39], v[180:183], v[204:207], v[36:39]
	v_mfma_f32_16x16x32_bf16 v[32:35], v[188:191], v[204:207], v[32:35]
	v_mfma_f32_16x16x32_bf16 v[20:23], v[180:183], v[222:225], v[20:23]
	v_mfma_f32_16x16x32_bf16 v[16:19], v[188:191], v[222:225], v[16:19]
	v_mfma_f32_16x16x32_bf16 v[4:7], v[180:183], v[230:233], v[4:7]
	v_mfma_f32_16x16x32_bf16 v[0:3], v[188:191], v[230:233], v[0:3]
	s_setprio 0
	s_barrier
	s_add_i32 s66, s66, 2
	s_add_u32 s64, s64, 0x100
	s_addc_u32 s65, s65, 0
	s_add_u32 s38, s38, 0x10000
	s_addc_u32 s39, s39, 0
	s_cmp_gt_u32 s66, 13
	s_cbranch_scc1 .LBB0_166

.LBB0_168:
	s_waitcnt vmcnt(8)
	v_pk_mul_f32 v[126:127], v[142:143], v[126:127] op_sel_hi:[0,1]
	v_pk_mul_f32 v[124:125], v[142:143], v[124:125] op_sel_hi:[0,1]
	v_pk_mul_f32 v[156:157], v[142:143], v[122:123] op_sel_hi:[0,1]
	v_pk_mul_f32 v[122:123], v[142:143], v[120:121] op_sel_hi:[0,1]
	v_cvt_pk_bf16_f32 v120, v124, v125
	v_cvt_pk_bf16_f32 v121, v126, v127
	v_cvt_pk_bf16_f32 v122, v122, v123
	v_cvt_pk_bf16_f32 v123, v156, v157
	ds_write_b128 v155, v[120:123]
	v_pk_mul_f32 v[118:119], v[142:143], v[118:119] op_sel_hi:[0,1]
	v_pk_mul_f32 v[116:117], v[142:143], v[116:117] op_sel_hi:[0,1]
	v_pk_mul_f32 v[120:121], v[142:143], v[114:115] op_sel_hi:[0,1]
	v_pk_mul_f32 v[114:115], v[142:143], v[112:113] op_sel_hi:[0,1]
	v_cvt_pk_bf16_f32 v112, v116, v117
	v_cvt_pk_bf16_f32 v113, v118, v119
	v_cvt_pk_bf16_f32 v114, v114, v115
	v_cvt_pk_bf16_f32 v115, v120, v121
	ds_write_b128 v155, v[112:115] offset:64
	v_add_u32_e32 v124, s3, v145
	v_mov_b64_e32 v[112:113], s[50:51]
	v_mad_i64_i32 v[122:123], s[38:39], v124, s6, v[112:113]
	s_lshl_b32 s38, s2, 8
	s_waitcnt lgkmcnt(0)
	s_ashr_i32 s39, s38, 31
	ds_read_b128 v[114:117], v158
	ds_read_b128 v[118:121], v158 offset:1152
	s_lshl_b64 s[38:39], s[38:39], 1
	v_lshl_add_u64 v[122:123], v[122:123], 0, s[38:39]
	v_lshl_add_u64 v[122:123], v[122:123], 0, s[0:1]
	v_lshl_add_u64 v[122:123], v[122:123], 0, v[208:209]
	s_movk_i32 s27, 0x7000
	s_waitcnt lgkmcnt(1)
	global_store_dwordx4 v[122:123], v[114:117], off nt
	v_pk_mul_f32 v[110:111], v[144:145], v[110:111] op_sel_hi:[0,1]
	v_pk_mul_f32 v[108:109], v[144:145], v[108:109] op_sel_hi:[0,1]
	v_add_co_u32_e32 v114, vcc, s27, v122
	v_pk_mul_f32 v[102:103], v[144:145], v[102:103] op_sel_hi:[0,1]
	s_nop 0
	v_addc_co_u32_e32 v115, vcc, 0, v123, vcc
	s_waitcnt lgkmcnt(0)
	global_store_dwordx4 v[114:115], v[118:121], off nt
	s_waitcnt lgkmcnt(0)
	v_pk_mul_f32 v[114:115], v[144:145], v[106:107] op_sel_hi:[0,1]
	v_pk_mul_f32 v[106:107], v[144:145], v[104:105] op_sel_hi:[0,1]
	v_cvt_pk_bf16_f32 v104, v108, v109
	v_cvt_pk_bf16_f32 v105, v110, v111
	v_cvt_pk_bf16_f32 v106, v106, v107
	v_cvt_pk_bf16_f32 v107, v114, v115
	ds_write_b128 v155, v[104:107]
	v_pk_mul_f32 v[104:105], v[144:145], v[98:99] op_sel_hi:[0,1]
	v_pk_mul_f32 v[98:99], v[144:145], v[96:97] op_sel_hi:[0,1]
	v_pk_mul_f32 v[100:101], v[144:145], v[100:101] op_sel_hi:[0,1]
	v_cvt_pk_bf16_f32 v96, v100, v101
	v_cvt_pk_bf16_f32 v97, v102, v103
	v_cvt_pk_bf16_f32 v98, v98, v99
	v_cvt_pk_bf16_f32 v99, v104, v105
	ds_write_b128 v155, v[96:99] offset:64
	s_waitcnt lgkmcnt(0)
	v_add_u32_e32 v104, s3, v147
	ds_read_b128 v[96:99], v158
	ds_read_b128 v[100:103], v158 offset:1152
	v_mad_i64_i32 v[104:105], s[40:41], v104, s6, v[112:113]
	v_lshl_add_u64 v[104:105], v[104:105], 0, s[38:39]
	v_lshl_add_u64 v[104:105], v[104:105], 0, s[0:1]
	v_lshl_add_u64 v[104:105], v[104:105], 0, v[208:209]
	s_waitcnt lgkmcnt(1)
	global_store_dwordx4 v[104:105], v[96:99], off nt
	v_pk_mul_f32 v[94:95], v[146:147], v[94:95] op_sel_hi:[0,1]
	v_pk_mul_f32 v[92:93], v[146:147], v[92:93] op_sel_hi:[0,1]
	v_add_co_u32_e32 v96, vcc, s27, v104
	v_pk_mul_f32 v[86:87], v[146:147], v[86:87] op_sel_hi:[0,1]
	s_nop 0
	v_addc_co_u32_e32 v97, vcc, 0, v105, vcc
	s_waitcnt lgkmcnt(0)
	global_store_dwordx4 v[96:97], v[100:103], off nt
	s_waitcnt lgkmcnt(0)
	v_pk_mul_f32 v[96:97], v[146:147], v[90:91] op_sel_hi:[0,1]
	v_pk_mul_f32 v[90:91], v[146:147], v[88:89] op_sel_hi:[0,1]
	v_cvt_pk_bf16_f32 v88, v92, v93
	v_cvt_pk_bf16_f32 v89, v94, v95
	v_cvt_pk_bf16_f32 v90, v90, v91
	v_cvt_pk_bf16_f32 v91, v96, v97
	ds_write_b128 v155, v[88:91]
	v_pk_mul_f32 v[88:89], v[146:147], v[82:83] op_sel_hi:[0,1]
	v_pk_mul_f32 v[82:83], v[146:147], v[80:81] op_sel_hi:[0,1]
	v_pk_mul_f32 v[84:85], v[146:147], v[84:85] op_sel_hi:[0,1]
	v_cvt_pk_bf16_f32 v80, v84, v85
	v_cvt_pk_bf16_f32 v81, v86, v87
	v_cvt_pk_bf16_f32 v82, v82, v83
	v_cvt_pk_bf16_f32 v83, v88, v89
	ds_write_b128 v155, v[80:83] offset:64
	s_waitcnt lgkmcnt(0)
	v_add_u32_e32 v88, s3, v149
	ds_read_b128 v[80:83], v158
	ds_read_b128 v[84:87], v158 offset:1152
	v_mad_i64_i32 v[88:89], s[40:41], v88, s6, v[112:113]
	v_lshl_add_u64 v[88:89], v[88:89], 0, s[38:39]
	v_lshl_add_u64 v[88:89], v[88:89], 0, s[0:1]
	v_lshl_add_u64 v[88:89], v[88:89], 0, v[208:209]
	s_waitcnt lgkmcnt(1)
	global_store_dwordx4 v[88:89], v[80:83], off nt
	v_pk_mul_f32 v[78:79], v[148:149], v[78:79] op_sel_hi:[0,1]
	v_pk_mul_f32 v[76:77], v[148:149], v[76:77] op_sel_hi:[0,1]
	v_add_co_u32_e32 v80, vcc, s27, v88
	v_pk_mul_f32 v[70:71], v[148:149], v[70:71] op_sel_hi:[0,1]
	s_nop 0
	v_addc_co_u32_e32 v81, vcc, 0, v89, vcc
	s_waitcnt lgkmcnt(0)
	global_store_dwordx4 v[80:81], v[84:87], off nt
	s_waitcnt lgkmcnt(0)
	v_pk_mul_f32 v[80:81], v[148:149], v[74:75] op_sel_hi:[0,1]
	v_pk_mul_f32 v[74:75], v[148:149], v[72:73] op_sel_hi:[0,1]
	v_cvt_pk_bf16_f32 v72, v76, v77
	v_cvt_pk_bf16_f32 v73, v78, v79
	v_cvt_pk_bf16_f32 v74, v74, v75
	v_cvt_pk_bf16_f32 v75, v80, v81
	ds_write_b128 v155, v[72:75]
	v_pk_mul_f32 v[72:73], v[148:149], v[66:67] op_sel_hi:[0,1]
	v_pk_mul_f32 v[66:67], v[148:149], v[64:65] op_sel_hi:[0,1]
	v_pk_mul_f32 v[68:69], v[148:149], v[68:69] op_sel_hi:[0,1]
	v_cvt_pk_bf16_f32 v64, v68, v69
	v_cvt_pk_bf16_f32 v65, v70, v71
	v_cvt_pk_bf16_f32 v66, v66, v67
	v_cvt_pk_bf16_f32 v67, v72, v73
	ds_write_b128 v155, v[64:67] offset:64
	s_waitcnt lgkmcnt(0)
	v_add_u32_e32 v72, s3, v151
	ds_read_b128 v[64:67], v158
	ds_read_b128 v[68:71], v158 offset:1152
	v_mad_i64_i32 v[72:73], s[2:3], v72, s6, v[112:113]
	v_lshl_add_u64 v[72:73], v[72:73], 0, s[38:39]
	v_lshl_add_u64 v[72:73], v[72:73], 0, s[0:1]
	v_lshl_add_u64 v[72:73], v[72:73], 0, v[208:209]
	s_waitcnt lgkmcnt(1)
	global_store_dwordx4 v[72:73], v[64:67], off nt
	v_pk_mul_f32 v[62:63], v[150:151], v[62:63] op_sel_hi:[0,1]
	v_pk_mul_f32 v[60:61], v[150:151], v[60:61] op_sel_hi:[0,1]
	v_add_co_u32_e32 v64, vcc, s27, v72
	v_pk_mul_f32 v[54:55], v[150:151], v[54:55] op_sel_hi:[0,1]
	s_nop 0
	v_addc_co_u32_e32 v65, vcc, 0, v73, vcc
	s_waitcnt lgkmcnt(0)
	global_store_dwordx4 v[64:65], v[68:71], off nt
	s_waitcnt lgkmcnt(0)
	v_pk_mul_f32 v[64:65], v[150:151], v[58:59] op_sel_hi:[0,1]
	v_pk_mul_f32 v[58:59], v[150:151], v[56:57] op_sel_hi:[0,1]
	v_cvt_pk_bf16_f32 v56, v60, v61
	v_cvt_pk_bf16_f32 v57, v62, v63
	v_cvt_pk_bf16_f32 v58, v58, v59
	v_cvt_pk_bf16_f32 v59, v64, v65
	ds_write_b128 v155, v[56:59]
	v_pk_mul_f32 v[56:57], v[150:151], v[50:51] op_sel_hi:[0,1]
	v_pk_mul_f32 v[50:51], v[150:151], v[48:49] op_sel_hi:[0,1]
	v_pk_mul_f32 v[52:53], v[150:151], v[52:53] op_sel_hi:[0,1]
	v_cvt_pk_bf16_f32 v48, v52, v53
	v_cvt_pk_bf16_f32 v49, v54, v55
	v_cvt_pk_bf16_f32 v50, v50, v51
	v_cvt_pk_bf16_f32 v51, v56, v57
	ds_write_b128 v155, v[48:51] offset:64
	s_waitcnt lgkmcnt(0)
	v_add_u32_e32 v56, 0x80, v124
	ds_read_b128 v[48:51], v158
	ds_read_b128 v[52:55], v158 offset:1152
	v_mad_i64_i32 v[56:57], s[2:3], v56, s6, v[112:113]
	v_lshl_add_u64 v[56:57], v[56:57], 0, s[38:39]
	v_lshl_add_u64 v[56:57], v[56:57], 0, s[0:1]
	v_lshl_add_u64 v[56:57], v[56:57], 0, v[208:209]
	s_waitcnt lgkmcnt(1)
	global_store_dwordx4 v[56:57], v[48:51], off nt
	v_pk_mul_f32 v[46:47], v[152:153], v[46:47] op_sel_hi:[0,1]
	v_pk_mul_f32 v[44:45], v[152:153], v[44:45] op_sel_hi:[0,1]
	v_add_co_u32_e32 v48, vcc, s27, v56
	v_pk_mul_f32 v[38:39], v[152:153], v[38:39] op_sel_hi:[0,1]
	s_nop 0
	v_addc_co_u32_e32 v49, vcc, 0, v57, vcc
	s_waitcnt lgkmcnt(0)
	global_store_dwordx4 v[48:49], v[52:55], off nt
	s_waitcnt lgkmcnt(0)
	v_pk_mul_f32 v[48:49], v[152:153], v[42:43] op_sel_hi:[0,1]
	v_pk_mul_f32 v[42:43], v[152:153], v[40:41] op_sel_hi:[0,1]
	v_cvt_pk_bf16_f32 v40, v44, v45
	v_cvt_pk_bf16_f32 v41, v46, v47
	v_cvt_pk_bf16_f32 v42, v42, v43
	v_cvt_pk_bf16_f32 v43, v48, v49
	ds_write_b128 v155, v[40:43]
	v_pk_mul_f32 v[40:41], v[152:153], v[34:35] op_sel_hi:[0,1]
	v_pk_mul_f32 v[34:35], v[152:153], v[32:33] op_sel_hi:[0,1]
	v_pk_mul_f32 v[36:37], v[152:153], v[36:37] op_sel_hi:[0,1]
	v_cvt_pk_bf16_f32 v32, v36, v37
	v_cvt_pk_bf16_f32 v33, v38, v39
	v_cvt_pk_bf16_f32 v34, v34, v35
	v_cvt_pk_bf16_f32 v35, v40, v41
	ds_write_b128 v155, v[32:35] offset:64
	s_waitcnt lgkmcnt(0)
	v_add_u32_e32 v40, 0x90, v124
	ds_read_b128 v[32:35], v158
	ds_read_b128 v[36:39], v158 offset:1152
	v_mad_i64_i32 v[40:41], s[2:3], v40, s6, v[112:113]
	v_lshl_add_u64 v[40:41], v[40:41], 0, s[38:39]
	v_lshl_add_u64 v[40:41], v[40:41], 0, s[0:1]
	v_lshl_add_u64 v[40:41], v[40:41], 0, v[208:209]
	s_waitcnt lgkmcnt(1)
	global_store_dwordx4 v[40:41], v[32:35], off nt
	v_pk_mul_f32 v[30:31], v[154:155], v[30:31] op_sel_hi:[0,1]
	v_pk_mul_f32 v[28:29], v[154:155], v[28:29] op_sel_hi:[0,1]
	v_add_co_u32_e32 v32, vcc, s27, v40
	v_pk_mul_f32 v[22:23], v[154:155], v[22:23] op_sel_hi:[0,1]
	s_nop 0
	v_addc_co_u32_e32 v33, vcc, 0, v41, vcc
	s_waitcnt lgkmcnt(0)
	global_store_dwordx4 v[32:33], v[36:39], off nt
	s_waitcnt lgkmcnt(0)
	v_pk_mul_f32 v[32:33], v[154:155], v[26:27] op_sel_hi:[0,1]
	v_pk_mul_f32 v[26:27], v[154:155], v[24:25] op_sel_hi:[0,1]
	v_cvt_pk_bf16_f32 v24, v28, v29
	v_cvt_pk_bf16_f32 v25, v30, v31
	v_cvt_pk_bf16_f32 v26, v26, v27
	v_cvt_pk_bf16_f32 v27, v32, v33
	ds_write_b128 v155, v[24:27]
	v_pk_mul_f32 v[24:25], v[154:155], v[18:19] op_sel_hi:[0,1]
	v_pk_mul_f32 v[18:19], v[154:155], v[16:17] op_sel_hi:[0,1]
	v_pk_mul_f32 v[20:21], v[154:155], v[20:21] op_sel_hi:[0,1]
	v_cvt_pk_bf16_f32 v16, v20, v21
	v_cvt_pk_bf16_f32 v17, v22, v23
	v_cvt_pk_bf16_f32 v18, v18, v19
	v_cvt_pk_bf16_f32 v19, v24, v25
	ds_write_b128 v155, v[16:19] offset:64
	s_waitcnt lgkmcnt(0)
	v_add_u32_e32 v24, 0xa0, v124
	ds_read_b128 v[16:19], v158
	ds_read_b128 v[20:23], v158 offset:1152
	v_mad_i64_i32 v[24:25], s[2:3], v24, s6, v[112:113]
	v_lshl_add_u64 v[24:25], v[24:25], 0, s[38:39]
	v_lshl_add_u64 v[24:25], v[24:25], 0, s[0:1]
	v_lshl_add_u64 v[24:25], v[24:25], 0, v[208:209]
	s_waitcnt lgkmcnt(1)
	global_store_dwordx4 v[24:25], v[16:19], off nt
	v_pk_mul_f32 v[14:15], v[140:141], v[14:15] op_sel_hi:[0,1]
	v_pk_mul_f32 v[12:13], v[140:141], v[12:13] op_sel_hi:[0,1]
	v_add_co_u32_e32 v16, vcc, s27, v24
	v_pk_mul_f32 v[6:7], v[140:141], v[6:7] op_sel_hi:[0,1]
	s_nop 0
	v_addc_co_u32_e32 v17, vcc, 0, v25, vcc
	s_waitcnt lgkmcnt(0)
	global_store_dwordx4 v[16:17], v[20:23], off nt
	s_waitcnt lgkmcnt(0)
	v_pk_mul_f32 v[16:17], v[140:141], v[10:11] op_sel_hi:[0,1]
	v_pk_mul_f32 v[10:11], v[140:141], v[8:9] op_sel_hi:[0,1]
	v_cvt_pk_bf16_f32 v8, v12, v13
	v_cvt_pk_bf16_f32 v9, v14, v15
	v_cvt_pk_bf16_f32 v10, v10, v11
	v_cvt_pk_bf16_f32 v11, v16, v17
	ds_write_b128 v155, v[8:11]
	v_pk_mul_f32 v[8:9], v[140:141], v[2:3] op_sel_hi:[0,1]
	v_pk_mul_f32 v[2:3], v[140:141], v[0:1] op_sel_hi:[0,1]
	v_pk_mul_f32 v[4:5], v[140:141], v[4:5] op_sel_hi:[0,1]
	v_cvt_pk_bf16_f32 v0, v4, v5
	v_cvt_pk_bf16_f32 v1, v6, v7
	v_cvt_pk_bf16_f32 v2, v2, v3
	v_cvt_pk_bf16_f32 v3, v8, v9
	ds_write_b128 v155, v[0:3] offset:64
	s_waitcnt lgkmcnt(0)
	v_add_u32_e32 v8, 0xb0, v124
	ds_read_b128 v[0:3], v158
	ds_read_b128 v[4:7], v158 offset:1152
	v_mad_i64_i32 v[8:9], s[2:3], v8, s6, v[112:113]
	v_lshl_add_u64 v[8:9], v[8:9], 0, s[38:39]
	v_lshl_add_u64 v[8:9], v[8:9], 0, s[0:1]
	v_lshl_add_u64 v[8:9], v[8:9], 0, v[208:209]
	s_waitcnt lgkmcnt(1)
	global_store_dwordx4 v[8:9], v[0:3], off nt
	s_movk_i32 s59, 0x7000
	s_mov_b64 s[2:3], -1
	v_add_co_u32_e32 v0, vcc, 0x7000, v8
	s_nop 1
	v_addc_co_u32_e32 v1, vcc, 0, v9, vcc
	s_waitcnt lgkmcnt(0)
	global_store_dwordx4 v[0:1], v[4:7], off nt
	s_waitcnt lgkmcnt(0)
	s_andn2_b64 vcc, exec, s[36:37]
	s_cbranch_vccnz .LBB0_159
	s_andn2_b64 vcc, exec, s[22:23]
	s_cbranch_vccnz .LBB0_158
	s_barrier
	s_branch .LBB0_158

.LBB0_433:
	s_ashr_i32 s61, s60, 31
	s_lshl_b64 s[2:3], s[60:61], 19
	s_add_u32 s70, s50, s2
	s_addc_u32 s71, s51, s3
	s_and_b64 s[2:3], s[36:37], exec
	s_cselect_b32 s2, s71, s35
	s_cselect_b32 s3, s70, s34
	s_ashr_i32 s57, s56, 31
	s_lshl_b64 s[40:41], s[56:57], 19
	s_add_u32 s76, s18, s40
	s_addc_u32 s77, s19, s41
	s_and_b64 s[40:41], s[36:37], exec
	s_cselect_b32 s23, s77, s79
	s_cselect_b32 s29, s76, s78
	s_add_u32 s34, s34, 0x40080
	s_addc_u32 s35, s35, 0
	s_add_u32 s42, s78, 0x100
	v_mov_b32_e32 v0, 0
	s_addc_u32 s43, s79, 0
	s_mov_b32 s44, -2
	s_add_u32 s38, s34, 0xfffc0080
	s_addc_u32 s39, s35, -1
	s_add_i32 s45, 0, 0x10000
	s_cmp_eq_u32 s44, 12
	s_cselect_b32 s41, s2, s39
	s_cselect_b32 s40, s3, s38
	s_cselect_b32 s39, s23, s43
	s_cselect_b32 s38, s29, s42
	s_add_i32 s57, 0, 0x14000
	v_add_u32_e32 v132, s45, v238
	v_add_u32_e32 v148, s57, v238
	ds_read_b128 v[112:115], v132
	ds_read_b128 v[116:119], v132 offset:1024
	ds_read_b128 v[120:123], v132 offset:2048
	ds_read_b128 v[132:135], v132 offset:3072
	ds_read_b128 v[136:139], v148
	ds_read_b128 v[140:143], v148 offset:1024
	ds_read_b128 v[144:147], v148 offset:2048
	ds_read_b128 v[148:151], v148 offset:3072
	v_lshl_add_u64 v[192:193], s[34:35], 0, v[224:225]
	s_add_i32 m0, s33, 0xc000
	ds_read_b128 v[152:155], v239
	ds_read_b128 v[156:159], v239 offset:1024
	ds_read_b128 v[168:171], v239 offset:2048
	ds_read_b128 v[172:175], v239 offset:3072
	ds_read_b128 v[176:179], v239 offset:4096
	ds_read_b128 v[180:183], v239 offset:5120
	ds_read_b128 v[184:187], v239 offset:6144
	ds_read_b128 v[188:191], v239 offset:7168
	global_load_lds_dwordx4 v[192:193], off
	v_lshl_add_u64 v[192:193], s[34:35], 0, v[226:227]
	s_add_i32 m0, s33, 0xe000
	s_nop 0
	global_load_lds_dwordx4 v[192:193], off
	s_waitcnt vmcnt(8)
	s_waitcnt lgkmcnt(0)
	s_barrier
	s_setprio 1
	s_waitcnt lgkmcnt(0)
	v_mfma_f32_16x16x32_bf16 v[164:167], v[112:115], v[152:155], 0
	v_mfma_f32_16x16x32_bf16 v[160:163], v[120:123], v[152:155], 0
	v_mfma_f32_16x16x32_bf16 v[108:111], v[112:115], v[168:171], 0
	v_mfma_f32_16x16x32_bf16 v[104:107], v[120:123], v[168:171], 0
	v_mfma_f32_16x16x32_bf16 v[92:95], v[112:115], v[176:179], 0
	v_mfma_f32_16x16x32_bf16 v[88:91], v[120:123], v[176:179], 0
	v_mfma_f32_16x16x32_bf16 v[76:79], v[112:115], v[184:187], 0
	v_mfma_f32_16x16x32_bf16 v[72:75], v[120:123], v[184:187], 0
	v_mfma_f32_16x16x32_bf16 v[164:167], v[116:119], v[156:159], v[164:167]
	v_mfma_f32_16x16x32_bf16 v[160:163], v[132:135], v[156:159], v[160:163]
	v_mfma_f32_16x16x32_bf16 v[108:111], v[116:119], v[172:175], v[108:111]
	v_mfma_f32_16x16x32_bf16 v[104:107], v[132:135], v[172:175], v[104:107]
	v_mfma_f32_16x16x32_bf16 v[92:95], v[116:119], v[180:183], v[92:95]
	v_mfma_f32_16x16x32_bf16 v[88:91], v[132:135], v[180:183], v[88:91]
	v_mfma_f32_16x16x32_bf16 v[76:79], v[116:119], v[188:191], v[76:79]
	v_mfma_f32_16x16x32_bf16 v[72:75], v[132:135], v[188:191], v[72:75]
	s_setprio 0
	s_setprio 1
	v_mfma_f32_16x16x32_bf16 v[128:131], v[136:139], v[152:155], 0
	v_mfma_f32_16x16x32_bf16 v[124:127], v[144:147], v[152:155], 0
	v_mfma_f32_16x16x32_bf16 v[100:103], v[136:139], v[168:171], 0
	v_mfma_f32_16x16x32_bf16 v[96:99], v[144:147], v[168:171], 0
	v_mfma_f32_16x16x32_bf16 v[84:87], v[136:139], v[176:179], 0
	v_mfma_f32_16x16x32_bf16 v[80:83], v[144:147], v[176:179], 0
	v_mfma_f32_16x16x32_bf16 v[68:71], v[136:139], v[184:187], 0
	v_mfma_f32_16x16x32_bf16 v[64:67], v[144:147], v[184:187], 0
	v_mfma_f32_16x16x32_bf16 v[128:131], v[140:143], v[156:159], v[128:131]
	v_mfma_f32_16x16x32_bf16 v[124:127], v[148:151], v[156:159], v[124:127]
	v_mfma_f32_16x16x32_bf16 v[100:103], v[140:143], v[172:175], v[100:103]
	v_mfma_f32_16x16x32_bf16 v[96:99], v[148:151], v[172:175], v[96:99]
	v_mfma_f32_16x16x32_bf16 v[84:87], v[140:143], v[180:183], v[84:87]
	v_mfma_f32_16x16x32_bf16 v[80:83], v[148:151], v[180:183], v[80:83]
	v_mfma_f32_16x16x32_bf16 v[68:71], v[140:143], v[188:191], v[68:71]
	v_mfma_f32_16x16x32_bf16 v[64:67], v[148:151], v[188:191], v[64:67]
	s_setprio 0
	s_barrier
	s_add_i32 s45, s45, s64
	v_lshl_add_u64 v[192:193], s[38:39], 0, v[208:209]
	s_mov_b32 m0, s45
	ds_read_b128 v[152:155], v239 offset:16384
	ds_read_b128 v[156:159], v239 offset:17408
	ds_read_b128 v[168:171], v239 offset:18432
	ds_read_b128 v[172:175], v239 offset:19456
	ds_read_b128 v[176:179], v239 offset:20480
	ds_read_b128 v[180:183], v239 offset:21504
	ds_read_b128 v[184:187], v239 offset:22528
	ds_read_b128 v[188:191], v239 offset:23552
	global_load_lds_dwordx4 v[192:193], off
	s_add_i32 m0, s45, 0x2000
	s_add_u32 s48, s38, 0x40000
	v_lshl_add_u64 v[194:195], s[38:39], 0, v[222:223]
	s_addc_u32 s49, s39, 0
	s_add_i32 s45, s57, s64
	global_load_lds_dwordx4 v[194:195], off
	v_lshl_add_u64 v[196:197], s[48:49], 0, v[208:209]
	s_mov_b32 m0, s45
	v_lshl_add_u64 v[198:199], s[40:41], 0, v[220:221]
	global_load_lds_dwordx4 v[196:197], off
	v_lshl_add_u64 v[196:197], s[48:49], 0, v[222:223]
	s_add_i32 m0, s45, 0x2000
	s_nop 0
	global_load_lds_dwordx4 v[196:197], off
	v_lshl_add_u64 v[196:197], s[40:41], 0, v[218:219]
	s_mov_b32 m0, s33
	s_nop 0
	global_load_lds_dwordx4 v[196:197], off
	s_mov_b32 m0, s11
	s_nop 0
	global_load_lds_dwordx4 v[198:199], off
	s_waitcnt vmcnt(8)
	s_waitcnt lgkmcnt(0)
	s_barrier
	s_setprio 1
	s_waitcnt lgkmcnt(0)
	v_mfma_f32_16x16x32_bf16 v[60:63], v[112:115], v[152:155], 0
	v_mfma_f32_16x16x32_bf16 v[56:59], v[120:123], v[152:155], 0
	v_mfma_f32_16x16x32_bf16 v[44:47], v[112:115], v[168:171], 0
	v_mfma_f32_16x16x32_bf16 v[40:43], v[120:123], v[168:171], 0
	v_mfma_f32_16x16x32_bf16 v[28:31], v[112:115], v[176:179], 0
	v_mfma_f32_16x16x32_bf16 v[24:27], v[120:123], v[176:179], 0
	v_mfma_f32_16x16x32_bf16 v[12:15], v[112:115], v[184:187], 0
	v_mfma_f32_16x16x32_bf16 v[8:11], v[120:123], v[184:187], 0
	v_mfma_f32_16x16x32_bf16 v[60:63], v[116:119], v[156:159], v[60:63]
	v_mfma_f32_16x16x32_bf16 v[56:59], v[132:135], v[156:159], v[56:59]
	v_mfma_f32_16x16x32_bf16 v[44:47], v[116:119], v[172:175], v[44:47]
	v_mfma_f32_16x16x32_bf16 v[40:43], v[132:135], v[172:175], v[40:43]
	v_mfma_f32_16x16x32_bf16 v[28:31], v[116:119], v[180:183], v[28:31]
	v_mfma_f32_16x16x32_bf16 v[24:27], v[132:135], v[180:183], v[24:27]
	v_mfma_f32_16x16x32_bf16 v[12:15], v[116:119], v[188:191], v[12:15]
	v_mfma_f32_16x16x32_bf16 v[8:11], v[132:135], v[188:191], v[8:11]
	s_setprio 0
	s_setprio 1
	v_mfma_f32_16x16x32_bf16 v[52:55], v[136:139], v[152:155], 0
	v_mfma_f32_16x16x32_bf16 v[48:51], v[144:147], v[152:155], 0
	v_mfma_f32_16x16x32_bf16 v[36:39], v[136:139], v[168:171], 0
	v_mfma_f32_16x16x32_bf16 v[32:35], v[144:147], v[168:171], 0
	v_mfma_f32_16x16x32_bf16 v[20:23], v[136:139], v[176:179], 0
	v_mfma_f32_16x16x32_bf16 v[16:19], v[144:147], v[176:179], 0
	v_mfma_f32_16x16x32_bf16 v[4:7], v[136:139], v[184:187], 0
	v_mfma_f32_16x16x32_bf16 v[0:3], v[144:147], v[184:187], 0
	v_mfma_f32_16x16x32_bf16 v[52:55], v[140:143], v[156:159], v[52:55]
	v_mfma_f32_16x16x32_bf16 v[48:51], v[148:151], v[156:159], v[48:51]
	v_mfma_f32_16x16x32_bf16 v[36:39], v[140:143], v[172:175], v[36:39]
	v_mfma_f32_16x16x32_bf16 v[32:35], v[148:151], v[172:175], v[32:35]
	v_mfma_f32_16x16x32_bf16 v[20:23], v[140:143], v[180:183], v[20:23]
	v_mfma_f32_16x16x32_bf16 v[16:19], v[148:151], v[180:183], v[16:19]
	v_mfma_f32_16x16x32_bf16 v[4:7], v[140:143], v[188:191], v[4:7]
	v_mfma_f32_16x16x32_bf16 v[0:3], v[148:151], v[188:191], v[0:3]
	s_setprio 0
	s_barrier
	s_branch .Lwout_mid

.Lwout_mid:
	s_add_i32 s45, 0, 0x18000
	s_add_i32 s48, 0, 0x1c000
	v_add_u32_e32 v132, s45, v238
	v_add_u32_e32 v148, s48, v238
	ds_read_b128 v[112:115], v132
	ds_read_b128 v[116:119], v132 offset:1024
	ds_read_b128 v[120:123], v132 offset:2048
	ds_read_b128 v[132:135], v132 offset:3072
	ds_read_b128 v[136:139], v148
	ds_read_b128 v[140:143], v148 offset:1024
	ds_read_b128 v[144:147], v148 offset:2048
	ds_read_b128 v[148:151], v148 offset:3072
	s_add_u32 s40, s40, 0x40000
	s_addc_u32 s41, s41, 0
	s_mov_b32 m0, s65
	v_lshl_add_u64 v[200:201], s[40:41], 0, v[218:219]
	ds_read_b128 v[152:155], v239 offset:32768
	ds_read_b128 v[156:159], v239 offset:33792
	ds_read_b128 v[168:171], v239 offset:34816
	ds_read_b128 v[172:175], v239 offset:35840
	ds_read_b128 v[176:179], v239 offset:36864
	ds_read_b128 v[180:183], v239 offset:37888
	ds_read_b128 v[184:187], v239 offset:38912
	ds_read_b128 v[188:191], v239 offset:39936
	global_load_lds_dwordx4 v[200:201], off
	v_lshl_add_u64 v[200:201], s[40:41], 0, v[220:221]
	s_mov_b32 m0, s66
	s_nop 0
	global_load_lds_dwordx4 v[200:201], off
	s_waitcnt vmcnt(8)
	s_waitcnt lgkmcnt(0)
	s_barrier
	s_setprio 1
	s_waitcnt lgkmcnt(0)
	v_mfma_f32_16x16x32_bf16 v[164:167], v[112:115], v[152:155], v[164:167]
	v_mfma_f32_16x16x32_bf16 v[160:163], v[120:123], v[152:155], v[160:163]
	v_mfma_f32_16x16x32_bf16 v[108:111], v[112:115], v[168:171], v[108:111]
	v_mfma_f32_16x16x32_bf16 v[104:107], v[120:123], v[168:171], v[104:107]
	v_mfma_f32_16x16x32_bf16 v[92:95], v[112:115], v[176:179], v[92:95]
	v_mfma_f32_16x16x32_bf16 v[88:91], v[120:123], v[176:179], v[88:91]
	v_mfma_f32_16x16x32_bf16 v[76:79], v[112:115], v[184:187], v[76:79]
	v_mfma_f32_16x16x32_bf16 v[72:75], v[120:123], v[184:187], v[72:75]
	v_mfma_f32_16x16x32_bf16 v[164:167], v[116:119], v[156:159], v[164:167]
	v_mfma_f32_16x16x32_bf16 v[160:163], v[132:135], v[156:159], v[160:163]
	v_mfma_f32_16x16x32_bf16 v[108:111], v[116:119], v[172:175], v[108:111]
	v_mfma_f32_16x16x32_bf16 v[104:107], v[132:135], v[172:175], v[104:107]
	v_mfma_f32_16x16x32_bf16 v[92:95], v[116:119], v[180:183], v[92:95]
	v_mfma_f32_16x16x32_bf16 v[88:91], v[132:135], v[180:183], v[88:91]
	v_mfma_f32_16x16x32_bf16 v[76:79], v[116:119], v[188:191], v[76:79]
	v_mfma_f32_16x16x32_bf16 v[72:75], v[132:135], v[188:191], v[72:75]
	s_setprio 0
	s_setprio 1
	v_mfma_f32_16x16x32_bf16 v[128:131], v[136:139], v[152:155], v[128:131]
	v_mfma_f32_16x16x32_bf16 v[124:127], v[144:147], v[152:155], v[124:127]
	v_mfma_f32_16x16x32_bf16 v[100:103], v[136:139], v[168:171], v[100:103]
	v_mfma_f32_16x16x32_bf16 v[96:99], v[144:147], v[168:171], v[96:99]
	v_mfma_f32_16x16x32_bf16 v[84:87], v[136:139], v[176:179], v[84:87]
	v_mfma_f32_16x16x32_bf16 v[80:83], v[144:147], v[176:179], v[80:83]
	v_mfma_f32_16x16x32_bf16 v[68:71], v[136:139], v[184:187], v[68:71]
	v_mfma_f32_16x16x32_bf16 v[64:67], v[144:147], v[184:187], v[64:67]
	v_mfma_f32_16x16x32_bf16 v[128:131], v[140:143], v[156:159], v[128:131]
	v_mfma_f32_16x16x32_bf16 v[124:127], v[148:151], v[156:159], v[124:127]
	v_mfma_f32_16x16x32_bf16 v[100:103], v[140:143], v[172:175], v[100:103]
	v_mfma_f32_16x16x32_bf16 v[96:99], v[148:151], v[172:175], v[96:99]
	v_mfma_f32_16x16x32_bf16 v[84:87], v[140:143], v[180:183], v[84:87]
	v_mfma_f32_16x16x32_bf16 v[80:83], v[148:151], v[180:183], v[80:83]
	v_mfma_f32_16x16x32_bf16 v[68:71], v[140:143], v[188:191], v[68:71]
	v_mfma_f32_16x16x32_bf16 v[64:67], v[148:151], v[188:191], v[64:67]
	s_setprio 0
	s_barrier
	s_add_i32 s40, s45, s64
	v_lshl_add_u64 v[192:193], v[192:193], 0, s[4:5]
	s_mov_b32 m0, s40
	ds_read_b128 v[152:155], v239 offset:49152
	ds_read_b128 v[156:159], v239 offset:50176
	ds_read_b128 v[168:171], v239 offset:51200
	ds_read_b128 v[172:175], v239 offset:52224
	ds_read_b128 v[176:179], v239 offset:53248
	ds_read_b128 v[180:183], v239 offset:54272
	ds_read_b128 v[184:187], v239 offset:55296
	ds_read_b128 v[188:191], v239 offset:56320
	global_load_lds_dwordx4 v[192:193], off
	s_add_i32 m0, s40, 0x2000
	s_add_u32 s38, s38, 0x40080
	v_lshl_add_u64 v[192:193], v[194:195], 0, s[4:5]
	s_addc_u32 s39, s39, 0
	s_add_i32 s40, s48, s64
	global_load_lds_dwordx4 v[192:193], off
	v_lshl_add_u64 v[192:193], s[38:39], 0, v[208:209]
	s_mov_b32 m0, s40
	s_nop 0
	global_load_lds_dwordx4 v[192:193], off
	v_lshl_add_u64 v[192:193], s[38:39], 0, v[222:223]
	s_add_i32 m0, s40, 0x2000
	s_nop 0
	global_load_lds_dwordx4 v[192:193], off
	v_lshl_add_u64 v[192:193], v[196:197], 0, s[4:5]
	s_mov_b32 m0, s74
	s_nop 0
	global_load_lds_dwordx4 v[192:193], off
	v_lshl_add_u64 v[192:193], v[198:199], 0, s[4:5]
	s_mov_b32 m0, s75
	s_nop 0
	global_load_lds_dwordx4 v[192:193], off
	s_waitcnt vmcnt(8)
	s_waitcnt lgkmcnt(0)
	s_barrier
	s_setprio 1
	s_waitcnt lgkmcnt(0)
	v_mfma_f32_16x16x32_bf16 v[60:63], v[112:115], v[152:155], v[60:63]
	v_mfma_f32_16x16x32_bf16 v[56:59], v[120:123], v[152:155], v[56:59]
	v_mfma_f32_16x16x32_bf16 v[44:47], v[112:115], v[168:171], v[44:47]
	v_mfma_f32_16x16x32_bf16 v[40:43], v[120:123], v[168:171], v[40:43]
	v_mfma_f32_16x16x32_bf16 v[28:31], v[112:115], v[176:179], v[28:31]
	v_mfma_f32_16x16x32_bf16 v[24:27], v[120:123], v[176:179], v[24:27]
	v_mfma_f32_16x16x32_bf16 v[12:15], v[112:115], v[184:187], v[12:15]
	v_mfma_f32_16x16x32_bf16 v[8:11], v[120:123], v[184:187], v[8:11]
	v_mfma_f32_16x16x32_bf16 v[60:63], v[116:119], v[156:159], v[60:63]
	v_mfma_f32_16x16x32_bf16 v[56:59], v[132:135], v[156:159], v[56:59]
	v_mfma_f32_16x16x32_bf16 v[44:47], v[116:119], v[172:175], v[44:47]
	v_mfma_f32_16x16x32_bf16 v[40:43], v[132:135], v[172:175], v[40:43]
	v_mfma_f32_16x16x32_bf16 v[28:31], v[116:119], v[180:183], v[28:31]
	v_mfma_f32_16x16x32_bf16 v[24:27], v[132:135], v[180:183], v[24:27]
	v_mfma_f32_16x16x32_bf16 v[12:15], v[116:119], v[188:191], v[12:15]
	v_mfma_f32_16x16x32_bf16 v[8:11], v[132:135], v[188:191], v[8:11]
	s_setprio 0
	s_setprio 1
	v_mfma_f32_16x16x32_bf16 v[52:55], v[136:139], v[152:155], v[52:55]
	v_mfma_f32_16x16x32_bf16 v[48:51], v[144:147], v[152:155], v[48:51]
	v_mfma_f32_16x16x32_bf16 v[36:39], v[136:139], v[168:171], v[36:39]
	v_mfma_f32_16x16x32_bf16 v[32:35], v[144:147], v[168:171], v[32:35]
	v_mfma_f32_16x16x32_bf16 v[20:23], v[136:139], v[176:179], v[20:23]
	v_mfma_f32_16x16x32_bf16 v[16:19], v[144:147], v[176:179], v[16:19]
	v_mfma_f32_16x16x32_bf16 v[4:7], v[136:139], v[184:187], v[4:7]
	v_mfma_f32_16x16x32_bf16 v[0:3], v[144:147], v[184:187], v[0:3]
	v_mfma_f32_16x16x32_bf16 v[52:55], v[140:143], v[156:159], v[52:55]
	v_mfma_f32_16x16x32_bf16 v[48:51], v[148:151], v[156:159], v[48:51]
	v_mfma_f32_16x16x32_bf16 v[36:39], v[140:143], v[172:175], v[36:39]
	v_mfma_f32_16x16x32_bf16 v[32:35], v[148:151], v[172:175], v[32:35]
	v_mfma_f32_16x16x32_bf16 v[20:23], v[140:143], v[180:183], v[20:23]
	v_mfma_f32_16x16x32_bf16 v[16:19], v[148:151], v[180:183], v[16:19]
	v_mfma_f32_16x16x32_bf16 v[4:7], v[140:143], v[188:191], v[4:7]
	v_mfma_f32_16x16x32_bf16 v[0:3], v[148:151], v[188:191], v[0:3]
	s_setprio 0
	s_barrier
	s_add_i32 s44, s44, 2
	s_add_u32 s42, s42, 0x100
	s_addc_u32 s43, s43, 0
	s_add_u32 s34, s34, 0x100
	s_addc_u32 s35, s35, 0
	s_cmp_gt_u32 s44, 13
	s_cbranch_scc0 .LBB0_434
	s_and_b64 vcc, exec, s[30:31]
	s_cbranch_vccz .LBB0_437
	s_barrier

.LBB0_570:
	s_ashr_i32 s29, s28, 31
	s_lshl_b64 s[30:31], s[28:29], 19
	s_add_u32 s30, s62, s30
	s_addc_u32 s31, s63, s31
	s_and_b64 s[34:35], s[36:37], exec
	s_cselect_b32 s3, s31, s43
	s_cselect_b32 s29, s30, s42
	s_ashr_i32 s27, s26, 31
	s_lshl_b64 s[34:35], s[26:27], 19
	s_add_u32 s34, s17, s34
	s_addc_u32 s35, s18, s35
	s_and_b64 s[44:45], s[36:37], exec
	s_cselect_b32 s27, s35, s41
	s_cselect_b32 s39, s34, s40
	s_add_u32 s61, s40, 0x100
	v_lshl_add_u32 v0, s38, 8, v158
	s_addc_u32 s64, s41, 0
	v_ashrrev_i32_e32 v1, 31, v0
	s_add_u32 s40, s42, 0xa000
	v_mov_b32_e32 v8, 0
	v_lshl_add_u64 v[156:157], v[0:1], 2, s[72:73]
	s_addc_u32 s41, s43, 0
	s_mov_b32 s65, -2
	s_mov_b64 s[42:43], 0
	s_add_u32 s44, s40, 0x6000
	s_addc_u32 s45, s41, 0
	s_and_b64 s[42:43], s[42:43], exec
	s_cselect_b32 s46, s29, s44
	s_cselect_b32 s47, s3, s45
	s_cselect_b32 s45, s27, s64
	s_cselect_b32 s44, s39, s61
	s_add_u32 s42, s46, 0x8000
	s_addc_u32 s43, s47, 0
	s_add_i32 s66, 0, 0x10000
	v_add_u32_e32 v169, s66, v159
	s_add_i32 s68, 0, 0x14000
	ds_read_b128 v[170:173], v169
	ds_read_b128 v[174:177], v169 offset:1024
	ds_read_b128 v[178:181], v169 offset:2048
	ds_read_b128 v[182:185], v169 offset:3072
	v_add_u32_e32 v169, s68, v159
	ds_read_b128 v[186:189], v169
	ds_read_b128 v[190:193], v169 offset:1024
	ds_read_b128 v[194:197], v169 offset:2048
	ds_read_b128 v[198:201], v169 offset:3072
	v_lshl_add_u64 v[206:207], s[40:41], 0, v[152:153]
	s_add_i32 m0, s48, 0xc000
	ds_read_b128 v[202:205], v160
	ds_read_b128 v[218:221], v160 offset:1024
	ds_read_b128 v[222:225], v160 offset:2048
	ds_read_b128 v[226:229], v160 offset:3072
	ds_read_b128 v[230:233], v160 offset:4096
	ds_read_b128 v[234:237], v160 offset:5120
	ds_read_b128 v[238:241], v160 offset:6144
	ds_read_b128 v[246:249], v160 offset:7168
	global_load_lds_dwordx4 v[206:207], off
	v_lshl_add_u64 v[206:207], s[40:41], 0, v[154:155]
	s_add_i32 m0, s48, 0xe000
	s_nop 0
	global_load_lds_dwordx4 v[206:207], off
	s_waitcnt vmcnt(8)
	s_waitcnt lgkmcnt(0)
	s_barrier
	s_setprio 1
	s_waitcnt lgkmcnt(0)
	v_mfma_f32_16x16x32_bf16 v[116:119], v[170:173], v[202:205], 0
	v_mfma_f32_16x16x32_bf16 v[124:127], v[178:181], v[202:205], 0
	v_mfma_f32_16x16x32_bf16 v[100:103], v[170:173], v[222:225], 0
	v_mfma_f32_16x16x32_bf16 v[108:111], v[178:181], v[222:225], 0
	v_mfma_f32_16x16x32_bf16 v[84:87], v[170:173], v[230:233], 0
	v_mfma_f32_16x16x32_bf16 v[92:95], v[178:181], v[230:233], 0
	v_mfma_f32_16x16x32_bf16 v[68:71], v[170:173], v[238:241], 0
	v_mfma_f32_16x16x32_bf16 v[76:79], v[178:181], v[238:241], 0
	v_mfma_f32_16x16x32_bf16 v[116:119], v[174:177], v[218:221], v[116:119]
	v_mfma_f32_16x16x32_bf16 v[124:127], v[182:185], v[218:221], v[124:127]
	v_mfma_f32_16x16x32_bf16 v[100:103], v[174:177], v[226:229], v[100:103]
	v_mfma_f32_16x16x32_bf16 v[108:111], v[182:185], v[226:229], v[108:111]
	v_mfma_f32_16x16x32_bf16 v[84:87], v[174:177], v[234:237], v[84:87]
	v_mfma_f32_16x16x32_bf16 v[92:95], v[182:185], v[234:237], v[92:95]
	v_mfma_f32_16x16x32_bf16 v[68:71], v[174:177], v[246:249], v[68:71]
	v_mfma_f32_16x16x32_bf16 v[76:79], v[182:185], v[246:249], v[76:79]
	s_setprio 0
	s_setprio 1
	v_mfma_f32_16x16x32_bf16 v[112:115], v[186:189], v[202:205], 0
	v_mfma_f32_16x16x32_bf16 v[120:123], v[194:197], v[202:205], 0
	v_mfma_f32_16x16x32_bf16 v[96:99], v[186:189], v[222:225], 0
	v_mfma_f32_16x16x32_bf16 v[104:107], v[194:197], v[222:225], 0
	v_mfma_f32_16x16x32_bf16 v[80:83], v[186:189], v[230:233], 0
	v_mfma_f32_16x16x32_bf16 v[88:91], v[194:197], v[230:233], 0
	v_mfma_f32_16x16x32_bf16 v[64:67], v[186:189], v[238:241], 0
	v_mfma_f32_16x16x32_bf16 v[72:75], v[194:197], v[238:241], 0
	v_mfma_f32_16x16x32_bf16 v[112:115], v[190:193], v[218:221], v[112:115]
	v_mfma_f32_16x16x32_bf16 v[120:123], v[198:201], v[218:221], v[120:123]
	v_mfma_f32_16x16x32_bf16 v[96:99], v[190:193], v[226:229], v[96:99]
	v_mfma_f32_16x16x32_bf16 v[104:107], v[198:201], v[226:229], v[104:107]
	v_mfma_f32_16x16x32_bf16 v[80:83], v[190:193], v[234:237], v[80:83]
	v_mfma_f32_16x16x32_bf16 v[88:91], v[198:201], v[234:237], v[88:91]
	v_mfma_f32_16x16x32_bf16 v[64:67], v[190:193], v[246:249], v[64:67]
	v_mfma_f32_16x16x32_bf16 v[72:75], v[198:201], v[246:249], v[72:75]
	s_setprio 0
	s_barrier
	s_add_i32 s66, s66, s19
	v_lshl_add_u64 v[206:207], s[44:45], 0, v[132:133]
	s_mov_b32 m0, s66
	ds_read_b128 v[202:205], v160 offset:16384
	ds_read_b128 v[218:221], v160 offset:17408
	ds_read_b128 v[222:225], v160 offset:18432
	ds_read_b128 v[226:229], v160 offset:19456
	ds_read_b128 v[230:233], v160 offset:20480
	ds_read_b128 v[234:237], v160 offset:21504
	ds_read_b128 v[238:241], v160 offset:22528
	ds_read_b128 v[246:249], v160 offset:23552
	global_load_lds_dwordx4 v[206:207], off
	s_add_i32 m0, s66, 0x2000
	s_add_u32 s66, s44, 0x40000
	v_lshl_add_u64 v[214:215], s[44:45], 0, v[128:129]
	s_addc_u32 s67, s45, 0
	s_add_i32 s68, s68, s19
	global_load_lds_dwordx4 v[214:215], off
	v_lshl_add_u64 v[216:217], s[66:67], 0, v[132:133]
	s_mov_b32 m0, s68
	s_nop 0
	global_load_lds_dwordx4 v[216:217], off
	v_lshl_add_u64 v[216:217], s[66:67], 0, v[128:129]
	s_add_i32 m0, s68, 0x2000
	s_nop 0
	global_load_lds_dwordx4 v[216:217], off
	v_lshl_add_u64 v[216:217], s[46:47], 0, v[134:135]
	s_mov_b32 m0, s48
	s_nop 0
	global_load_lds_dwordx4 v[216:217], off
	v_lshl_add_u64 v[216:217], s[46:47], 0, v[130:131]
	s_mov_b32 m0, s49
	s_nop 0
	global_load_lds_dwordx4 v[216:217], off
	s_waitcnt vmcnt(8)
	s_waitcnt lgkmcnt(0)
	s_barrier
	s_setprio 1
	s_waitcnt lgkmcnt(0)
	v_mfma_f32_16x16x32_bf16 v[52:55], v[170:173], v[202:205], 0
	v_mfma_f32_16x16x32_bf16 v[60:63], v[178:181], v[202:205], 0
	v_mfma_f32_16x16x32_bf16 v[36:39], v[170:173], v[222:225], 0
	v_mfma_f32_16x16x32_bf16 v[44:47], v[178:181], v[222:225], 0
	v_mfma_f32_16x16x32_bf16 v[20:23], v[170:173], v[230:233], 0
	v_mfma_f32_16x16x32_bf16 v[28:31], v[178:181], v[230:233], 0
	v_mfma_f32_16x16x32_bf16 v[4:7], v[170:173], v[238:241], 0
	v_mfma_f32_16x16x32_bf16 v[12:15], v[178:181], v[238:241], 0
	v_mfma_f32_16x16x32_bf16 v[52:55], v[174:177], v[218:221], v[52:55]
	v_mfma_f32_16x16x32_bf16 v[60:63], v[182:185], v[218:221], v[60:63]
	v_mfma_f32_16x16x32_bf16 v[36:39], v[174:177], v[226:229], v[36:39]
	v_mfma_f32_16x16x32_bf16 v[44:47], v[182:185], v[226:229], v[44:47]
	v_mfma_f32_16x16x32_bf16 v[20:23], v[174:177], v[234:237], v[20:23]
	v_mfma_f32_16x16x32_bf16 v[28:31], v[182:185], v[234:237], v[28:31]
	v_mfma_f32_16x16x32_bf16 v[4:7], v[174:177], v[246:249], v[4:7]
	v_mfma_f32_16x16x32_bf16 v[12:15], v[182:185], v[246:249], v[12:15]
	s_setprio 0
	s_setprio 1
	v_mfma_f32_16x16x32_bf16 v[48:51], v[186:189], v[202:205], 0
	v_mfma_f32_16x16x32_bf16 v[56:59], v[194:197], v[202:205], 0
	v_mfma_f32_16x16x32_bf16 v[32:35], v[186:189], v[222:225], 0
	v_mfma_f32_16x16x32_bf16 v[40:43], v[194:197], v[222:225], 0
	v_mfma_f32_16x16x32_bf16 v[16:19], v[186:189], v[230:233], 0
	v_mfma_f32_16x16x32_bf16 v[24:27], v[194:197], v[230:233], 0
	v_mfma_f32_16x16x32_bf16 v[0:3], v[186:189], v[238:241], 0
	v_mfma_f32_16x16x32_bf16 v[8:11], v[194:197], v[238:241], 0
	v_mfma_f32_16x16x32_bf16 v[48:51], v[190:193], v[218:221], v[48:51]
	v_mfma_f32_16x16x32_bf16 v[56:59], v[198:201], v[218:221], v[56:59]
	v_mfma_f32_16x16x32_bf16 v[32:35], v[190:193], v[226:229], v[32:35]
	v_mfma_f32_16x16x32_bf16 v[40:43], v[198:201], v[226:229], v[40:43]
	v_mfma_f32_16x16x32_bf16 v[16:19], v[190:193], v[234:237], v[16:19]
	v_mfma_f32_16x16x32_bf16 v[24:27], v[198:201], v[234:237], v[24:27]
	v_mfma_f32_16x16x32_bf16 v[0:3], v[190:193], v[246:249], v[0:3]
	v_mfma_f32_16x16x32_bf16 v[8:11], v[198:201], v[246:249], v[8:11]
	s_setprio 0
	s_barrier
	s_branch .Lgu_mid
.LBB0_571:
	s_add_u32 s44, s40, 0x6000
	s_addc_u32 s45, s41, 0
	s_and_b64 s[42:43], s[42:43], exec
	s_cselect_b32 s46, s29, s44
	s_cselect_b32 s47, s3, s45
	s_cselect_b32 s45, s27, s64
	s_cselect_b32 s44, s39, s61
	s_add_u32 s42, s46, 0x8000
	s_addc_u32 s43, s47, 0
	s_add_i32 s66, 0, 0x10000
	v_add_u32_e32 v169, s66, v159
	s_add_i32 s68, 0, 0x14000
	ds_read_b128 v[170:173], v169
	ds_read_b128 v[174:177], v169 offset:1024
	ds_read_b128 v[178:181], v169 offset:2048
	ds_read_b128 v[182:185], v169 offset:3072
	v_add_u32_e32 v169, s68, v159
	ds_read_b128 v[186:189], v169
	ds_read_b128 v[190:193], v169 offset:1024
	ds_read_b128 v[194:197], v169 offset:2048
	ds_read_b128 v[198:201], v169 offset:3072
	v_lshl_add_u64 v[206:207], s[40:41], 0, v[152:153]
	s_add_i32 m0, s48, 0xc000
	ds_read_b128 v[202:205], v160
	ds_read_b128 v[218:221], v160 offset:1024
	ds_read_b128 v[222:225], v160 offset:2048
	ds_read_b128 v[226:229], v160 offset:3072
	ds_read_b128 v[230:233], v160 offset:4096
	ds_read_b128 v[234:237], v160 offset:5120
	ds_read_b128 v[238:241], v160 offset:6144
	ds_read_b128 v[246:249], v160 offset:7168
	global_load_lds_dwordx4 v[206:207], off
	v_lshl_add_u64 v[206:207], s[40:41], 0, v[154:155]
	s_add_i32 m0, s48, 0xe000
	s_nop 0
	global_load_lds_dwordx4 v[206:207], off
	s_waitcnt vmcnt(8)
	s_waitcnt lgkmcnt(0)
	s_barrier
	s_setprio 1
	s_waitcnt lgkmcnt(0)
	v_mfma_f32_16x16x32_bf16 v[116:119], v[170:173], v[202:205], v[116:119]
	v_mfma_f32_16x16x32_bf16 v[124:127], v[178:181], v[202:205], v[124:127]
	v_mfma_f32_16x16x32_bf16 v[100:103], v[170:173], v[222:225], v[100:103]
	v_mfma_f32_16x16x32_bf16 v[108:111], v[178:181], v[222:225], v[108:111]
	v_mfma_f32_16x16x32_bf16 v[84:87], v[170:173], v[230:233], v[84:87]
	v_mfma_f32_16x16x32_bf16 v[92:95], v[178:181], v[230:233], v[92:95]
	v_mfma_f32_16x16x32_bf16 v[68:71], v[170:173], v[238:241], v[68:71]
	v_mfma_f32_16x16x32_bf16 v[76:79], v[178:181], v[238:241], v[76:79]
	v_mfma_f32_16x16x32_bf16 v[116:119], v[174:177], v[218:221], v[116:119]
	v_mfma_f32_16x16x32_bf16 v[124:127], v[182:185], v[218:221], v[124:127]
	v_mfma_f32_16x16x32_bf16 v[100:103], v[174:177], v[226:229], v[100:103]
	v_mfma_f32_16x16x32_bf16 v[108:111], v[182:185], v[226:229], v[108:111]
	v_mfma_f32_16x16x32_bf16 v[84:87], v[174:177], v[234:237], v[84:87]
	v_mfma_f32_16x16x32_bf16 v[92:95], v[182:185], v[234:237], v[92:95]
	v_mfma_f32_16x16x32_bf16 v[68:71], v[174:177], v[246:249], v[68:71]
	v_mfma_f32_16x16x32_bf16 v[76:79], v[182:185], v[246:249], v[76:79]
	s_setprio 0
	s_setprio 1
	v_mfma_f32_16x16x32_bf16 v[112:115], v[186:189], v[202:205], v[112:115]
	v_mfma_f32_16x16x32_bf16 v[120:123], v[194:197], v[202:205], v[120:123]
	v_mfma_f32_16x16x32_bf16 v[96:99], v[186:189], v[222:225], v[96:99]
	v_mfma_f32_16x16x32_bf16 v[104:107], v[194:197], v[222:225], v[104:107]
	v_mfma_f32_16x16x32_bf16 v[80:83], v[186:189], v[230:233], v[80:83]
	v_mfma_f32_16x16x32_bf16 v[88:91], v[194:197], v[230:233], v[88:91]
	v_mfma_f32_16x16x32_bf16 v[64:67], v[186:189], v[238:241], v[64:67]
	v_mfma_f32_16x16x32_bf16 v[72:75], v[194:197], v[238:241], v[72:75]
	v_mfma_f32_16x16x32_bf16 v[112:115], v[190:193], v[218:221], v[112:115]
	v_mfma_f32_16x16x32_bf16 v[120:123], v[198:201], v[218:221], v[120:123]
	v_mfma_f32_16x16x32_bf16 v[96:99], v[190:193], v[226:229], v[96:99]
	v_mfma_f32_16x16x32_bf16 v[104:107], v[198:201], v[226:229], v[104:107]
	v_mfma_f32_16x16x32_bf16 v[80:83], v[190:193], v[234:237], v[80:83]
	v_mfma_f32_16x16x32_bf16 v[88:91], v[198:201], v[234:237], v[88:91]
	v_mfma_f32_16x16x32_bf16 v[64:67], v[190:193], v[246:249], v[64:67]
	v_mfma_f32_16x16x32_bf16 v[72:75], v[198:201], v[246:249], v[72:75]
	s_setprio 0
	s_barrier
	s_add_i32 s66, s66, s19
	v_lshl_add_u64 v[206:207], s[44:45], 0, v[132:133]
	s_mov_b32 m0, s66
	ds_read_b128 v[202:205], v160 offset:16384
	ds_read_b128 v[218:221], v160 offset:17408
	ds_read_b128 v[222:225], v160 offset:18432
	ds_read_b128 v[226:229], v160 offset:19456
	ds_read_b128 v[230:233], v160 offset:20480
	ds_read_b128 v[234:237], v160 offset:21504
	ds_read_b128 v[238:241], v160 offset:22528
	ds_read_b128 v[246:249], v160 offset:23552
	global_load_lds_dwordx4 v[206:207], off
	s_add_i32 m0, s66, 0x2000
	s_add_u32 s66, s44, 0x40000
	v_lshl_add_u64 v[214:215], s[44:45], 0, v[128:129]
	s_addc_u32 s67, s45, 0
	s_add_i32 s68, s68, s19
	global_load_lds_dwordx4 v[214:215], off
	v_lshl_add_u64 v[216:217], s[66:67], 0, v[132:133]
	s_mov_b32 m0, s68
	s_nop 0
	global_load_lds_dwordx4 v[216:217], off
	v_lshl_add_u64 v[216:217], s[66:67], 0, v[128:129]
	s_add_i32 m0, s68, 0x2000
	s_nop 0
	global_load_lds_dwordx4 v[216:217], off
	v_lshl_add_u64 v[216:217], s[46:47], 0, v[134:135]
	s_mov_b32 m0, s48
	s_nop 0
	global_load_lds_dwordx4 v[216:217], off
	v_lshl_add_u64 v[216:217], s[46:47], 0, v[130:131]
	s_mov_b32 m0, s49
	s_nop 0
	global_load_lds_dwordx4 v[216:217], off
	s_waitcnt vmcnt(8)
	s_waitcnt lgkmcnt(0)
	s_barrier
	s_setprio 1
	s_waitcnt lgkmcnt(0)
	v_mfma_f32_16x16x32_bf16 v[52:55], v[170:173], v[202:205], v[52:55]
	v_mfma_f32_16x16x32_bf16 v[60:63], v[178:181], v[202:205], v[60:63]
	v_mfma_f32_16x16x32_bf16 v[36:39], v[170:173], v[222:225], v[36:39]
	v_mfma_f32_16x16x32_bf16 v[44:47], v[178:181], v[222:225], v[44:47]
	v_mfma_f32_16x16x32_bf16 v[20:23], v[170:173], v[230:233], v[20:23]
	v_mfma_f32_16x16x32_bf16 v[28:31], v[178:181], v[230:233], v[28:31]
	v_mfma_f32_16x16x32_bf16 v[4:7], v[170:173], v[238:241], v[4:7]
	v_mfma_f32_16x16x32_bf16 v[12:15], v[178:181], v[238:241], v[12:15]
	v_mfma_f32_16x16x32_bf16 v[52:55], v[174:177], v[218:221], v[52:55]
	v_mfma_f32_16x16x32_bf16 v[60:63], v[182:185], v[218:221], v[60:63]
	v_mfma_f32_16x16x32_bf16 v[36:39], v[174:177], v[226:229], v[36:39]
	v_mfma_f32_16x16x32_bf16 v[44:47], v[182:185], v[226:229], v[44:47]
	v_mfma_f32_16x16x32_bf16 v[20:23], v[174:177], v[234:237], v[20:23]
	v_mfma_f32_16x16x32_bf16 v[28:31], v[182:185], v[234:237], v[28:31]
	v_mfma_f32_16x16x32_bf16 v[4:7], v[174:177], v[246:249], v[4:7]
	v_mfma_f32_16x16x32_bf16 v[12:15], v[182:185], v[246:249], v[12:15]
	s_setprio 0
	s_setprio 1
	v_mfma_f32_16x16x32_bf16 v[48:51], v[186:189], v[202:205], v[48:51]
	v_mfma_f32_16x16x32_bf16 v[56:59], v[194:197], v[202:205], v[56:59]
	v_mfma_f32_16x16x32_bf16 v[32:35], v[186:189], v[222:225], v[32:35]
	v_mfma_f32_16x16x32_bf16 v[40:43], v[194:197], v[222:225], v[40:43]
	v_mfma_f32_16x16x32_bf16 v[16:19], v[186:189], v[230:233], v[16:19]
	v_mfma_f32_16x16x32_bf16 v[24:27], v[194:197], v[230:233], v[24:27]
	v_mfma_f32_16x16x32_bf16 v[0:3], v[186:189], v[238:241], v[0:3]
	v_mfma_f32_16x16x32_bf16 v[8:11], v[194:197], v[238:241], v[8:11]
	v_mfma_f32_16x16x32_bf16 v[48:51], v[190:193], v[218:221], v[48:51]
	v_mfma_f32_16x16x32_bf16 v[56:59], v[198:201], v[218:221], v[56:59]
	v_mfma_f32_16x16x32_bf16 v[32:35], v[190:193], v[226:229], v[32:35]
	v_mfma_f32_16x16x32_bf16 v[40:43], v[198:201], v[226:229], v[40:43]
	v_mfma_f32_16x16x32_bf16 v[16:19], v[190:193], v[234:237], v[16:19]
	v_mfma_f32_16x16x32_bf16 v[24:27], v[198:201], v[234:237], v[24:27]
	v_mfma_f32_16x16x32_bf16 v[0:3], v[190:193], v[246:249], v[0:3]
	v_mfma_f32_16x16x32_bf16 v[8:11], v[198:201], v[246:249], v[8:11]
	s_setprio 0
	s_barrier
.Lgu_mid:
	s_add_i32 s66, 0, 0x18000
	v_add_u32_e32 v169, s66, v159
	s_add_i32 s67, 0, 0x1c000
	ds_read_b128 v[170:173], v169
	ds_read_b128 v[174:177], v169 offset:1024
	ds_read_b128 v[178:181], v169 offset:2048
	ds_read_b128 v[182:185], v169 offset:3072
	v_add_u32_e32 v169, s67, v159
	ds_read_b128 v[186:189], v169
	ds_read_b128 v[190:193], v169 offset:1024
	ds_read_b128 v[194:197], v169 offset:2048
	ds_read_b128 v[198:201], v169 offset:3072
	s_add_u32 s46, s46, 0x2000
	s_addc_u32 s47, s47, 0
	s_mov_b32 m0, s52
	v_lshl_add_u64 v[216:217], s[46:47], 0, v[134:135]
	ds_read_b128 v[202:205], v160 offset:32768
	ds_read_b128 v[218:221], v160 offset:33792
	ds_read_b128 v[222:225], v160 offset:34816
	ds_read_b128 v[226:229], v160 offset:35840
	ds_read_b128 v[230:233], v160 offset:36864
	ds_read_b128 v[234:237], v160 offset:37888
	ds_read_b128 v[238:241], v160 offset:38912
	ds_read_b128 v[246:249], v160 offset:39936
	global_load_lds_dwordx4 v[216:217], off
	v_lshl_add_u64 v[216:217], s[46:47], 0, v[130:131]
	s_mov_b32 m0, s53
	s_nop 0
	global_load_lds_dwordx4 v[216:217], off
	s_waitcnt vmcnt(8)
	s_waitcnt lgkmcnt(0)
	s_barrier
	s_setprio 1
	s_waitcnt lgkmcnt(0)
	v_mfma_f32_16x16x32_bf16 v[116:119], v[170:173], v[202:205], v[116:119]
	v_mfma_f32_16x16x32_bf16 v[124:127], v[178:181], v[202:205], v[124:127]
	v_mfma_f32_16x16x32_bf16 v[100:103], v[170:173], v[222:225], v[100:103]
	v_mfma_f32_16x16x32_bf16 v[108:111], v[178:181], v[222:225], v[108:111]
	v_mfma_f32_16x16x32_bf16 v[84:87], v[170:173], v[230:233], v[84:87]
	v_mfma_f32_16x16x32_bf16 v[92:95], v[178:181], v[230:233], v[92:95]
	v_mfma_f32_16x16x32_bf16 v[68:71], v[170:173], v[238:241], v[68:71]
	v_mfma_f32_16x16x32_bf16 v[76:79], v[178:181], v[238:241], v[76:79]
	v_mfma_f32_16x16x32_bf16 v[116:119], v[174:177], v[218:221], v[116:119]
	v_mfma_f32_16x16x32_bf16 v[124:127], v[182:185], v[218:221], v[124:127]
	v_mfma_f32_16x16x32_bf16 v[100:103], v[174:177], v[226:229], v[100:103]
	v_mfma_f32_16x16x32_bf16 v[108:111], v[182:185], v[226:229], v[108:111]
	v_mfma_f32_16x16x32_bf16 v[84:87], v[174:177], v[234:237], v[84:87]
	v_mfma_f32_16x16x32_bf16 v[92:95], v[182:185], v[234:237], v[92:95]
	v_mfma_f32_16x16x32_bf16 v[68:71], v[174:177], v[246:249], v[68:71]
	v_mfma_f32_16x16x32_bf16 v[76:79], v[182:185], v[246:249], v[76:79]
	s_setprio 0
	s_setprio 1
	v_mfma_f32_16x16x32_bf16 v[112:115], v[186:189], v[202:205], v[112:115]
	v_mfma_f32_16x16x32_bf16 v[120:123], v[194:197], v[202:205], v[120:123]
	v_mfma_f32_16x16x32_bf16 v[96:99], v[186:189], v[222:225], v[96:99]
	v_mfma_f32_16x16x32_bf16 v[104:107], v[194:197], v[222:225], v[104:107]
	v_mfma_f32_16x16x32_bf16 v[80:83], v[186:189], v[230:233], v[80:83]
	v_mfma_f32_16x16x32_bf16 v[88:91], v[194:197], v[230:233], v[88:91]
	v_mfma_f32_16x16x32_bf16 v[64:67], v[186:189], v[238:241], v[64:67]
	v_mfma_f32_16x16x32_bf16 v[72:75], v[194:197], v[238:241], v[72:75]
	v_mfma_f32_16x16x32_bf16 v[112:115], v[190:193], v[218:221], v[112:115]
	v_mfma_f32_16x16x32_bf16 v[120:123], v[198:201], v[218:221], v[120:123]
	v_mfma_f32_16x16x32_bf16 v[96:99], v[190:193], v[226:229], v[96:99]
	v_mfma_f32_16x16x32_bf16 v[104:107], v[198:201], v[226:229], v[104:107]
	v_mfma_f32_16x16x32_bf16 v[80:83], v[190:193], v[234:237], v[80:83]
	v_mfma_f32_16x16x32_bf16 v[88:91], v[198:201], v[234:237], v[88:91]
	v_mfma_f32_16x16x32_bf16 v[64:67], v[190:193], v[246:249], v[64:67]
	v_mfma_f32_16x16x32_bf16 v[72:75], v[198:201], v[246:249], v[72:75]
	s_setprio 0
	s_barrier
	s_add_i32 s46, s66, s19
	v_lshl_add_u64 v[206:207], v[206:207], 0, s[4:5]
	s_mov_b32 m0, s46
	ds_read_b128 v[202:205], v160 offset:49152
	ds_read_b128 v[218:221], v160 offset:50176
	ds_read_b128 v[222:225], v160 offset:51200
	ds_read_b128 v[226:229], v160 offset:52224
	ds_read_b128 v[230:233], v160 offset:53248
	ds_read_b128 v[234:237], v160 offset:54272
	ds_read_b128 v[238:241], v160 offset:55296
	ds_read_b128 v[246:249], v160 offset:56320
	global_load_lds_dwordx4 v[206:207], off
	s_add_i32 m0, s46, 0x2000
	s_add_u32 s44, s44, 0x40080
	v_lshl_add_u64 v[206:207], v[214:215], 0, s[4:5]
	s_addc_u32 s45, s45, 0
	s_add_i32 s46, s67, s19
	global_load_lds_dwordx4 v[206:207], off
	v_lshl_add_u64 v[206:207], s[44:45], 0, v[132:133]
	s_mov_b32 m0, s46
	s_nop 0
	global_load_lds_dwordx4 v[206:207], off
	v_lshl_add_u64 v[206:207], s[44:45], 0, v[128:129]
	s_add_i32 m0, s46, 0x2000
	s_nop 0
	global_load_lds_dwordx4 v[206:207], off
	v_lshl_add_u64 v[206:207], s[42:43], 0, v[134:135]
	s_mov_b32 m0, s0
	s_nop 0
	global_load_lds_dwordx4 v[206:207], off
	v_lshl_add_u64 v[206:207], s[42:43], 0, v[130:131]
	s_mov_b32 m0, s56
	s_nop 0
	global_load_lds_dwordx4 v[206:207], off
	s_waitcnt vmcnt(8)
	s_waitcnt lgkmcnt(0)
	s_barrier
	s_setprio 1
	s_waitcnt lgkmcnt(0)
	v_mfma_f32_16x16x32_bf16 v[52:55], v[170:173], v[202:205], v[52:55]
	v_mfma_f32_16x16x32_bf16 v[60:63], v[178:181], v[202:205], v[60:63]
	v_mfma_f32_16x16x32_bf16 v[36:39], v[170:173], v[222:225], v[36:39]
	v_mfma_f32_16x16x32_bf16 v[44:47], v[178:181], v[222:225], v[44:47]
	v_mfma_f32_16x16x32_bf16 v[20:23], v[170:173], v[230:233], v[20:23]
	v_mfma_f32_16x16x32_bf16 v[28:31], v[178:181], v[230:233], v[28:31]
	v_mfma_f32_16x16x32_bf16 v[4:7], v[170:173], v[238:241], v[4:7]
	v_mfma_f32_16x16x32_bf16 v[12:15], v[178:181], v[238:241], v[12:15]
	v_mfma_f32_16x16x32_bf16 v[52:55], v[174:177], v[218:221], v[52:55]
	v_mfma_f32_16x16x32_bf16 v[60:63], v[182:185], v[218:221], v[60:63]
	v_mfma_f32_16x16x32_bf16 v[36:39], v[174:177], v[226:229], v[36:39]
	v_mfma_f32_16x16x32_bf16 v[44:47], v[182:185], v[226:229], v[44:47]
	v_mfma_f32_16x16x32_bf16 v[20:23], v[174:177], v[234:237], v[20:23]
	v_mfma_f32_16x16x32_bf16 v[28:31], v[182:185], v[234:237], v[28:31]
	v_mfma_f32_16x16x32_bf16 v[4:7], v[174:177], v[246:249], v[4:7]
	v_mfma_f32_16x16x32_bf16 v[12:15], v[182:185], v[246:249], v[12:15]
	s_setprio 0
	s_setprio 1
	v_mfma_f32_16x16x32_bf16 v[48:51], v[186:189], v[202:205], v[48:51]
	v_mfma_f32_16x16x32_bf16 v[56:59], v[194:197], v[202:205], v[56:59]
	v_mfma_f32_16x16x32_bf16 v[32:35], v[186:189], v[222:225], v[32:35]
	v_mfma_f32_16x16x32_bf16 v[40:43], v[194:197], v[222:225], v[40:43]
	v_mfma_f32_16x16x32_bf16 v[16:19], v[186:189], v[230:233], v[16:19]
	v_mfma_f32_16x16x32_bf16 v[24:27], v[194:197], v[230:233], v[24:27]
	v_mfma_f32_16x16x32_bf16 v[0:3], v[186:189], v[238:241], v[0:3]
	v_mfma_f32_16x16x32_bf16 v[8:11], v[194:197], v[238:241], v[8:11]
	v_mfma_f32_16x16x32_bf16 v[48:51], v[190:193], v[218:221], v[48:51]
	v_mfma_f32_16x16x32_bf16 v[56:59], v[198:201], v[218:221], v[56:59]
	v_mfma_f32_16x16x32_bf16 v[32:35], v[190:193], v[226:229], v[32:35]
	v_mfma_f32_16x16x32_bf16 v[40:43], v[198:201], v[226:229], v[40:43]
	v_mfma_f32_16x16x32_bf16 v[16:19], v[190:193], v[234:237], v[16:19]
	v_mfma_f32_16x16x32_bf16 v[24:27], v[198:201], v[234:237], v[24:27]
	v_mfma_f32_16x16x32_bf16 v[0:3], v[190:193], v[246:249], v[0:3]
	v_mfma_f32_16x16x32_bf16 v[8:11], v[198:201], v[246:249], v[8:11]
	s_setprio 0
	s_barrier
	s_add_i32 s65, s65, 2
	s_add_u32 s61, s61, 0x100
	s_addc_u32 s64, s64, 0
	s_add_u32 s40, s40, 0x10000
	s_addc_u32 s41, s41, 0
	s_cmp_gt_u32 s65, 13
	s_cbranch_scc1 .LBB0_574

.LBB0_576:
	s_waitcnt vmcnt(8)
	v_mul_f32_e32 v170, 0xbfb8aa3b, v168
	v_pk_mul_f32 v[176:177], v[170:171], v[116:117] op_sel_hi:[0,1]
	v_exp_f32_e32 v169, v176
	v_pk_mul_f32 v[120:121], v[124:125], v[120:121]
	v_pk_mul_f32 v[124:125], v[170:171], v[124:125] op_sel_hi:[0,1]
	v_pk_mul_f32 v[122:123], v[126:127], v[122:123]
	v_pk_mul_f32 v[174:175], v[170:171], v[118:119] op_sel_hi:[0,1]
	v_pk_mul_f32 v[126:127], v[170:171], v[126:127] op_sel_hi:[0,1]
	v_exp_f32_e32 v170, v124
	v_add_f32_e32 v124, 1.0, v169
	v_exp_f32_e32 v169, v177
	v_exp_f32_e32 v171, v125
	v_exp_f32_e32 v173, v126
	s_mul_i32 s3, s38, 22
	v_add_f32_e32 v125, 1.0, v169
	v_exp_f32_e32 v169, v174
	s_add_i32 s2, s3, s2
	s_ashr_i32 s3, s2, 31
	v_rcp_f32_e32 v124, v124
	v_add_f32_e32 v126, 1.0, v169
	v_exp_f32_e32 v169, v175
	v_exp_f32_e32 v175, v127
	v_add_f32_e32 v170, 1.0, v170
	v_rcp_f32_e32 v125, v125
	v_add_f32_e32 v127, 1.0, v169
	v_add_f32_e32 v171, 1.0, v171
	v_rcp_f32_e32 v126, v126
	v_rcp_f32_e32 v127, v127
	s_lshl_b64 s[2:3], s[2:3], 16
	v_rcp_f32_e32 v170, v170
	v_rcp_f32_e32 v171, v171
	v_add_f32_e32 v173, 1.0, v173
	v_add_f32_e32 v169, 1.0, v175
	s_add_u32 s38, s50, s2
	v_mul_f32_e32 v172, v168, v168
	v_rcp_f32_e32 v174, v173
	v_rcp_f32_e32 v175, v169
	v_pk_mul_f32 v[114:115], v[118:119], v[114:115]
	v_pk_mul_f32 v[112:113], v[116:117], v[112:113]
	s_addc_u32 s39, s51, s3
	v_pk_mul_f32 v[112:113], v[172:173], v[112:113] op_sel_hi:[0,1]
	v_pk_mul_f32 v[114:115], v[172:173], v[114:115] op_sel_hi:[0,1]
	v_lshl_add_u64 v[156:157], s[38:39], 0, v[136:137]
	v_pk_mul_f32 v[116:117], v[172:173], v[120:121] op_sel_hi:[0,1]
	v_pk_mul_f32 v[114:115], v[126:127], v[114:115]
	v_pk_mul_f32 v[112:113], v[124:125], v[112:113]
	v_lshl_add_u64 v[156:157], v[156:157], 0, v[208:209]
	v_pk_mul_f32 v[118:119], v[172:173], v[122:123] op_sel_hi:[0,1]
	v_pk_mul_f32 v[116:117], v[170:171], v[116:117]
	v_cvt_pk_bf16_f32 v112, v112, v113
	v_cvt_pk_bf16_f32 v113, v114, v115
	v_pk_mul_f32 v[118:119], v[174:175], v[118:119]
	v_cvt_pk_bf16_f32 v114, v116, v117
	v_pk_mul_f32 v[104:105], v[108:109], v[104:105]
	v_cvt_pk_bf16_f32 v115, v118, v119
	global_store_dwordx4 v[156:157], v[112:115], off nt
	v_pk_mul_f32 v[106:107], v[110:111], v[106:107]
	v_mul_f32_e32 v116, v167, v167
	v_mul_f32_e32 v114, 0xbfb8aa3b, v167
	v_pk_mul_f32 v[120:121], v[114:115], v[100:101] op_sel_hi:[0,1]
	v_pk_mul_f32 v[118:119], v[114:115], v[102:103] op_sel_hi:[0,1]
	v_exp_f32_e32 v115, v120
	v_exp_f32_e32 v118, v118
	v_exp_f32_e32 v119, v119
	v_pk_mul_f32 v[98:99], v[102:103], v[98:99]
	v_pk_mul_f32 v[108:109], v[114:115], v[108:109] op_sel_hi:[0,1]
	v_pk_mul_f32 v[110:111], v[114:115], v[110:111] op_sel_hi:[0,1]
	v_exp_f32_e32 v114, v108
	v_add_f32_e32 v108, 1.0, v115
	v_exp_f32_e32 v115, v121
	v_exp_f32_e32 v117, v109
	v_exp_f32_e32 v120, v111
	v_add_f32_e32 v111, 1.0, v119
	v_add_f32_e32 v109, 1.0, v115
	v_add_f32_e32 v115, 1.0, v117
	v_exp_f32_e32 v117, v110
	v_add_f32_e32 v110, 1.0, v118
	v_rcp_f32_e32 v108, v108
	v_add_f32_e32 v114, 1.0, v114
	v_rcp_f32_e32 v109, v109
	v_rcp_f32_e32 v110, v110
	v_add_f32_e32 v117, 1.0, v117
	v_rcp_f32_e32 v111, v111
	v_rcp_f32_e32 v114, v114
	v_rcp_f32_e32 v115, v115
	v_rcp_f32_e32 v118, v117
	v_add_f32_e32 v117, 1.0, v120
	v_rcp_f32_e32 v119, v117
	v_pk_mul_f32 v[96:97], v[100:101], v[96:97]
	v_pk_mul_f32 v[98:99], v[116:117], v[98:99] op_sel_hi:[0,1]
	v_pk_mul_f32 v[96:97], v[116:117], v[96:97] op_sel_hi:[0,1]
	v_lshl_add_u64 v[112:113], s[38:39], 0, v[138:139]
	v_pk_mul_f32 v[100:101], v[116:117], v[104:105] op_sel_hi:[0,1]
	v_pk_mul_f32 v[98:99], v[110:111], v[98:99]
	v_pk_mul_f32 v[96:97], v[108:109], v[96:97]
	v_lshl_add_u64 v[112:113], v[112:113], 0, v[208:209]
	v_pk_mul_f32 v[102:103], v[116:117], v[106:107] op_sel_hi:[0,1]
	v_pk_mul_f32 v[100:101], v[114:115], v[100:101]
	v_cvt_pk_bf16_f32 v96, v96, v97
	v_cvt_pk_bf16_f32 v97, v98, v99
	v_pk_mul_f32 v[102:103], v[118:119], v[102:103]
	v_cvt_pk_bf16_f32 v98, v100, v101
	v_pk_mul_f32 v[88:89], v[92:93], v[88:89]
	v_cvt_pk_bf16_f32 v99, v102, v103
	global_store_dwordx4 v[112:113], v[96:99], off nt
	v_pk_mul_f32 v[90:91], v[94:95], v[90:91]
	v_mul_f32_e32 v100, v166, v166
	v_mul_f32_e32 v98, 0xbfb8aa3b, v166
	v_pk_mul_f32 v[104:105], v[98:99], v[84:85] op_sel_hi:[0,1]
	v_pk_mul_f32 v[102:103], v[98:99], v[86:87] op_sel_hi:[0,1]
	v_exp_f32_e32 v99, v104
	v_exp_f32_e32 v102, v102
	v_exp_f32_e32 v103, v103
	v_pk_mul_f32 v[82:83], v[86:87], v[82:83]
	v_pk_mul_f32 v[92:93], v[98:99], v[92:93] op_sel_hi:[0,1]
	v_pk_mul_f32 v[94:95], v[98:99], v[94:95] op_sel_hi:[0,1]
	v_exp_f32_e32 v98, v92
	v_add_f32_e32 v92, 1.0, v99
	v_exp_f32_e32 v99, v105
	v_exp_f32_e32 v101, v93
	v_exp_f32_e32 v104, v95
	v_add_f32_e32 v95, 1.0, v103
	v_add_f32_e32 v93, 1.0, v99
	v_add_f32_e32 v99, 1.0, v101
	v_exp_f32_e32 v101, v94
	v_add_f32_e32 v94, 1.0, v102
	v_rcp_f32_e32 v92, v92
	v_add_f32_e32 v98, 1.0, v98
	v_rcp_f32_e32 v93, v93
	v_rcp_f32_e32 v94, v94
	v_add_f32_e32 v101, 1.0, v101
	v_rcp_f32_e32 v95, v95
	v_rcp_f32_e32 v98, v98
	v_rcp_f32_e32 v99, v99
	v_rcp_f32_e32 v102, v101
	v_add_f32_e32 v101, 1.0, v104
	v_rcp_f32_e32 v103, v101
	v_pk_mul_f32 v[80:81], v[84:85], v[80:81]
	v_pk_mul_f32 v[82:83], v[100:101], v[82:83] op_sel_hi:[0,1]
	v_pk_mul_f32 v[80:81], v[100:101], v[80:81] op_sel_hi:[0,1]
	v_lshl_add_u64 v[96:97], s[38:39], 0, v[140:141]
	v_pk_mul_f32 v[84:85], v[100:101], v[88:89] op_sel_hi:[0,1]
	v_pk_mul_f32 v[82:83], v[94:95], v[82:83]
	v_pk_mul_f32 v[80:81], v[92:93], v[80:81]
	v_lshl_add_u64 v[96:97], v[96:97], 0, v[208:209]
	v_pk_mul_f32 v[86:87], v[100:101], v[90:91] op_sel_hi:[0,1]
	v_pk_mul_f32 v[84:85], v[98:99], v[84:85]
	v_cvt_pk_bf16_f32 v80, v80, v81
	v_cvt_pk_bf16_f32 v81, v82, v83
	v_pk_mul_f32 v[86:87], v[102:103], v[86:87]
	v_cvt_pk_bf16_f32 v82, v84, v85
	v_pk_mul_f32 v[72:73], v[76:77], v[72:73]
	v_cvt_pk_bf16_f32 v83, v86, v87
	global_store_dwordx4 v[96:97], v[80:83], off nt
	v_pk_mul_f32 v[74:75], v[78:79], v[74:75]
	v_mul_f32_e32 v84, v165, v165
	v_mul_f32_e32 v82, 0xbfb8aa3b, v165
	v_pk_mul_f32 v[88:89], v[82:83], v[68:69] op_sel_hi:[0,1]
	v_pk_mul_f32 v[86:87], v[82:83], v[70:71] op_sel_hi:[0,1]
	v_exp_f32_e32 v83, v88
	v_exp_f32_e32 v86, v86
	v_exp_f32_e32 v87, v87
	v_pk_mul_f32 v[66:67], v[70:71], v[66:67]
	v_pk_mul_f32 v[76:77], v[82:83], v[76:77] op_sel_hi:[0,1]
	v_pk_mul_f32 v[78:79], v[82:83], v[78:79] op_sel_hi:[0,1]
	v_exp_f32_e32 v82, v76
	v_add_f32_e32 v76, 1.0, v83
	v_exp_f32_e32 v83, v89
	v_exp_f32_e32 v85, v77
	v_exp_f32_e32 v88, v79
	v_add_f32_e32 v79, 1.0, v87
	v_add_f32_e32 v77, 1.0, v83
	v_add_f32_e32 v83, 1.0, v85
	v_exp_f32_e32 v85, v78
	v_add_f32_e32 v78, 1.0, v86
	v_rcp_f32_e32 v76, v76
	v_add_f32_e32 v82, 1.0, v82
	v_rcp_f32_e32 v77, v77
	v_rcp_f32_e32 v78, v78
	v_add_f32_e32 v85, 1.0, v85
	v_rcp_f32_e32 v79, v79
	v_rcp_f32_e32 v82, v82
	v_rcp_f32_e32 v83, v83
	v_rcp_f32_e32 v86, v85
	v_add_f32_e32 v85, 1.0, v88
	v_rcp_f32_e32 v87, v85
	v_pk_mul_f32 v[64:65], v[68:69], v[64:65]
	v_pk_mul_f32 v[66:67], v[84:85], v[66:67] op_sel_hi:[0,1]
	v_pk_mul_f32 v[64:65], v[84:85], v[64:65] op_sel_hi:[0,1]
	v_lshl_add_u64 v[80:81], s[38:39], 0, v[142:143]
	v_pk_mul_f32 v[68:69], v[84:85], v[72:73] op_sel_hi:[0,1]
	v_pk_mul_f32 v[66:67], v[78:79], v[66:67]
	v_pk_mul_f32 v[64:65], v[76:77], v[64:65]
	v_lshl_add_u64 v[80:81], v[80:81], 0, v[208:209]
	v_pk_mul_f32 v[70:71], v[84:85], v[74:75] op_sel_hi:[0,1]
	v_pk_mul_f32 v[68:69], v[82:83], v[68:69]
	v_cvt_pk_bf16_f32 v64, v64, v65
	v_cvt_pk_bf16_f32 v65, v66, v67
	v_pk_mul_f32 v[70:71], v[86:87], v[70:71]
	v_cvt_pk_bf16_f32 v66, v68, v69
	v_pk_mul_f32 v[56:57], v[60:61], v[56:57]
	v_cvt_pk_bf16_f32 v67, v70, v71
	global_store_dwordx4 v[80:81], v[64:67], off nt
	v_pk_mul_f32 v[58:59], v[62:63], v[58:59]
	v_mul_f32_e32 v68, v164, v164
	v_mul_f32_e32 v66, 0xbfb8aa3b, v164
	v_pk_mul_f32 v[72:73], v[66:67], v[52:53] op_sel_hi:[0,1]
	v_pk_mul_f32 v[70:71], v[66:67], v[54:55] op_sel_hi:[0,1]
	v_exp_f32_e32 v67, v72
	v_exp_f32_e32 v70, v70
	v_exp_f32_e32 v71, v71
	v_pk_mul_f32 v[50:51], v[54:55], v[50:51]
	v_pk_mul_f32 v[60:61], v[66:67], v[60:61] op_sel_hi:[0,1]
	v_pk_mul_f32 v[62:63], v[66:67], v[62:63] op_sel_hi:[0,1]
	v_exp_f32_e32 v66, v60
	v_add_f32_e32 v60, 1.0, v67
	v_exp_f32_e32 v67, v73
	v_exp_f32_e32 v69, v61
	v_exp_f32_e32 v72, v63
	v_add_f32_e32 v63, 1.0, v71
	v_add_f32_e32 v61, 1.0, v67
	v_add_f32_e32 v67, 1.0, v69
	v_exp_f32_e32 v69, v62
	v_add_f32_e32 v62, 1.0, v70
	v_rcp_f32_e32 v60, v60
	v_add_f32_e32 v66, 1.0, v66
	v_rcp_f32_e32 v61, v61
	v_rcp_f32_e32 v62, v62
	v_add_f32_e32 v69, 1.0, v69
	v_rcp_f32_e32 v63, v63
	v_rcp_f32_e32 v66, v66
	v_rcp_f32_e32 v67, v67
	v_rcp_f32_e32 v70, v69
	v_add_f32_e32 v69, 1.0, v72
	v_rcp_f32_e32 v71, v69
	v_pk_mul_f32 v[48:49], v[52:53], v[48:49]
	v_pk_mul_f32 v[50:51], v[68:69], v[50:51] op_sel_hi:[0,1]
	v_pk_mul_f32 v[48:49], v[68:69], v[48:49] op_sel_hi:[0,1]
	v_lshl_add_u64 v[64:65], s[38:39], 0, v[144:145]
	v_pk_mul_f32 v[52:53], v[68:69], v[56:57] op_sel_hi:[0,1]
	v_pk_mul_f32 v[50:51], v[62:63], v[50:51]
	v_pk_mul_f32 v[48:49], v[60:61], v[48:49]
	v_lshl_add_u64 v[64:65], v[64:65], 0, v[208:209]
	v_pk_mul_f32 v[54:55], v[68:69], v[58:59] op_sel_hi:[0,1]
	v_pk_mul_f32 v[52:53], v[66:67], v[52:53]
	v_cvt_pk_bf16_f32 v48, v48, v49
	v_cvt_pk_bf16_f32 v49, v50, v51
	v_pk_mul_f32 v[54:55], v[70:71], v[54:55]
	v_cvt_pk_bf16_f32 v50, v52, v53
	v_pk_mul_f32 v[40:41], v[44:45], v[40:41]
	v_cvt_pk_bf16_f32 v51, v54, v55
	global_store_dwordx4 v[64:65], v[48:51], off nt
	v_pk_mul_f32 v[42:43], v[46:47], v[42:43]
	v_mul_f32_e32 v52, v163, v163
	v_mul_f32_e32 v50, 0xbfb8aa3b, v163
	v_pk_mul_f32 v[56:57], v[50:51], v[36:37] op_sel_hi:[0,1]
	v_pk_mul_f32 v[54:55], v[50:51], v[38:39] op_sel_hi:[0,1]
	v_exp_f32_e32 v51, v56
	v_exp_f32_e32 v54, v54
	v_exp_f32_e32 v55, v55
	v_pk_mul_f32 v[34:35], v[38:39], v[34:35]
	v_pk_mul_f32 v[44:45], v[50:51], v[44:45] op_sel_hi:[0,1]
	v_pk_mul_f32 v[46:47], v[50:51], v[46:47] op_sel_hi:[0,1]
	v_exp_f32_e32 v50, v44
	v_add_f32_e32 v44, 1.0, v51
	v_exp_f32_e32 v51, v57
	v_exp_f32_e32 v53, v45
	v_exp_f32_e32 v56, v47
	v_add_f32_e32 v47, 1.0, v55
	v_add_f32_e32 v45, 1.0, v51
	v_add_f32_e32 v51, 1.0, v53
	v_exp_f32_e32 v53, v46
	v_add_f32_e32 v46, 1.0, v54
	v_rcp_f32_e32 v44, v44
	v_add_f32_e32 v50, 1.0, v50
	v_rcp_f32_e32 v45, v45
	v_rcp_f32_e32 v46, v46
	v_add_f32_e32 v53, 1.0, v53
	v_rcp_f32_e32 v47, v47
	v_rcp_f32_e32 v50, v50
	v_rcp_f32_e32 v51, v51
	v_rcp_f32_e32 v54, v53
	v_add_f32_e32 v53, 1.0, v56
	v_rcp_f32_e32 v55, v53
	v_pk_mul_f32 v[32:33], v[36:37], v[32:33]
	v_pk_mul_f32 v[34:35], v[52:53], v[34:35] op_sel_hi:[0,1]
	v_pk_mul_f32 v[32:33], v[52:53], v[32:33] op_sel_hi:[0,1]
	v_lshl_add_u64 v[48:49], s[38:39], 0, v[146:147]
	v_pk_mul_f32 v[36:37], v[52:53], v[40:41] op_sel_hi:[0,1]
	v_pk_mul_f32 v[34:35], v[46:47], v[34:35]
	v_pk_mul_f32 v[32:33], v[44:45], v[32:33]
	v_lshl_add_u64 v[48:49], v[48:49], 0, v[208:209]
	v_pk_mul_f32 v[38:39], v[52:53], v[42:43] op_sel_hi:[0,1]
	v_pk_mul_f32 v[36:37], v[50:51], v[36:37]
	v_cvt_pk_bf16_f32 v32, v32, v33
	v_cvt_pk_bf16_f32 v33, v34, v35
	v_pk_mul_f32 v[38:39], v[54:55], v[38:39]
	v_cvt_pk_bf16_f32 v34, v36, v37
	v_pk_mul_f32 v[24:25], v[28:29], v[24:25]
	v_cvt_pk_bf16_f32 v35, v38, v39
	global_store_dwordx4 v[48:49], v[32:35], off nt
	v_pk_mul_f32 v[26:27], v[30:31], v[26:27]
	v_mul_f32_e32 v36, v162, v162
	v_mul_f32_e32 v34, 0xbfb8aa3b, v162
	v_pk_mul_f32 v[40:41], v[34:35], v[20:21] op_sel_hi:[0,1]
	v_pk_mul_f32 v[38:39], v[34:35], v[22:23] op_sel_hi:[0,1]
	v_exp_f32_e32 v35, v40
	v_exp_f32_e32 v38, v38
	v_exp_f32_e32 v39, v39
	v_pk_mul_f32 v[18:19], v[22:23], v[18:19]
	v_pk_mul_f32 v[28:29], v[34:35], v[28:29] op_sel_hi:[0,1]
	v_pk_mul_f32 v[30:31], v[34:35], v[30:31] op_sel_hi:[0,1]
	v_exp_f32_e32 v34, v28
	v_add_f32_e32 v28, 1.0, v35
	v_exp_f32_e32 v35, v41
	v_exp_f32_e32 v37, v29
	v_exp_f32_e32 v40, v31
	v_add_f32_e32 v31, 1.0, v39
	v_add_f32_e32 v29, 1.0, v35
	v_add_f32_e32 v35, 1.0, v37
	v_exp_f32_e32 v37, v30
	v_add_f32_e32 v30, 1.0, v38
	v_rcp_f32_e32 v28, v28
	v_add_f32_e32 v34, 1.0, v34
	v_rcp_f32_e32 v29, v29
	v_rcp_f32_e32 v30, v30
	v_add_f32_e32 v37, 1.0, v37
	v_rcp_f32_e32 v31, v31
	v_rcp_f32_e32 v34, v34
	v_rcp_f32_e32 v35, v35
	v_rcp_f32_e32 v38, v37
	v_add_f32_e32 v37, 1.0, v40
	v_rcp_f32_e32 v39, v37
	v_pk_mul_f32 v[16:17], v[20:21], v[16:17]
	v_pk_mul_f32 v[18:19], v[36:37], v[18:19] op_sel_hi:[0,1]
	v_pk_mul_f32 v[16:17], v[36:37], v[16:17] op_sel_hi:[0,1]
	v_lshl_add_u64 v[32:33], s[38:39], 0, v[148:149]
	v_pk_mul_f32 v[20:21], v[36:37], v[24:25] op_sel_hi:[0,1]
	v_pk_mul_f32 v[18:19], v[30:31], v[18:19]
	v_pk_mul_f32 v[16:17], v[28:29], v[16:17]
	v_lshl_add_u64 v[32:33], v[32:33], 0, v[208:209]
	v_pk_mul_f32 v[22:23], v[36:37], v[26:27] op_sel_hi:[0,1]
	v_pk_mul_f32 v[20:21], v[34:35], v[20:21]
	v_cvt_pk_bf16_f32 v16, v16, v17
	v_cvt_pk_bf16_f32 v17, v18, v19
	v_pk_mul_f32 v[22:23], v[38:39], v[22:23]
	v_cvt_pk_bf16_f32 v18, v20, v21
	v_pk_mul_f32 v[8:9], v[12:13], v[8:9]
	v_cvt_pk_bf16_f32 v19, v22, v23
	global_store_dwordx4 v[32:33], v[16:19], off nt
	v_pk_mul_f32 v[10:11], v[14:15], v[10:11]
	v_mul_f32_e32 v20, v161, v161
	v_mul_f32_e32 v18, 0xbfb8aa3b, v161
	v_pk_mul_f32 v[24:25], v[18:19], v[4:5] op_sel_hi:[0,1]
	v_pk_mul_f32 v[22:23], v[18:19], v[6:7] op_sel_hi:[0,1]
	v_exp_f32_e32 v19, v24
	v_exp_f32_e32 v22, v22
	v_exp_f32_e32 v23, v23
	v_pk_mul_f32 v[2:3], v[6:7], v[2:3]
	v_pk_mul_f32 v[12:13], v[18:19], v[12:13] op_sel_hi:[0,1]
	v_pk_mul_f32 v[14:15], v[18:19], v[14:15] op_sel_hi:[0,1]
	v_exp_f32_e32 v18, v12
	v_add_f32_e32 v12, 1.0, v19
	v_exp_f32_e32 v19, v25
	v_exp_f32_e32 v21, v13
	v_exp_f32_e32 v24, v15
	v_add_f32_e32 v15, 1.0, v23
	v_add_f32_e32 v13, 1.0, v19
	v_add_f32_e32 v19, 1.0, v21
	v_exp_f32_e32 v21, v14
	v_add_f32_e32 v14, 1.0, v22
	v_rcp_f32_e32 v12, v12
	v_add_f32_e32 v18, 1.0, v18
	v_add_f32_e32 v21, 1.0, v21
	v_rcp_f32_e32 v13, v13
	v_rcp_f32_e32 v14, v14
	v_rcp_f32_e32 v22, v21
	v_rcp_f32_e32 v15, v15
	v_add_f32_e32 v21, 1.0, v24
	v_rcp_f32_e32 v18, v18
	v_rcp_f32_e32 v19, v19
	v_rcp_f32_e32 v23, v21
	v_pk_mul_f32 v[0:1], v[4:5], v[0:1]
	v_lshl_add_u64 v[16:17], s[38:39], 0, v[150:151]
	v_pk_mul_f32 v[0:1], v[20:21], v[0:1] op_sel_hi:[0,1]
	v_pk_mul_f32 v[2:3], v[20:21], v[2:3] op_sel_hi:[0,1]
	v_lshl_add_u64 v[16:17], v[16:17], 0, v[208:209]
	v_pk_mul_f32 v[4:5], v[20:21], v[8:9] op_sel_hi:[0,1]
	v_pk_mul_f32 v[6:7], v[20:21], v[10:11] op_sel_hi:[0,1]
	v_pk_mul_f32 v[2:3], v[14:15], v[2:3]
	v_pk_mul_f32 v[0:1], v[12:13], v[0:1]
	s_andn2_b64 vcc, exec, s[36:37]
	s_mov_b64 s[2:3], -1
	v_pk_mul_f32 v[6:7], v[22:23], v[6:7]
	v_pk_mul_f32 v[4:5], v[18:19], v[4:5]
	v_cvt_pk_bf16_f32 v0, v0, v1
	v_cvt_pk_bf16_f32 v1, v2, v3
	s_nop 0
	v_cvt_pk_bf16_f32 v2, v4, v5
	v_cvt_pk_bf16_f32 v3, v6, v7
	global_store_dwordx4 v[16:17], v[0:3], off nt
	s_cbranch_vccnz .LBB0_567
	s_andn2_b64 vcc, exec, s[22:23]
	s_cbranch_vccnz .LBB0_566
	s_barrier
	s_branch .LBB0_566

.LBB0_653:
	s_add_u32 s34, s34, 0xa000
	s_addc_u32 s35, s35, 0
	s_add_u32 s2, s78, 0x100
	v_mov_b32_e32 v0, 0
	s_addc_u32 s3, s79, 0
	s_mov_b32 s27, -2
	s_waitcnt lgkmcnt(0)
	s_add_u32 s38, s34, 0x6000
	s_addc_u32 s39, s35, 0
	s_cmp_eq_u32 s27, 40
	s_cselect_b32 s42, s56, s38
	s_cselect_b32 s43, s57, s39
	s_cselect_b32 s40, s60, s2
	s_cselect_b32 s41, s61, s3
	s_add_u32 s38, s42, 0x8000
	s_addc_u32 s39, s43, 0
	s_add_i32 s44, 0, 0x10000
	s_add_i32 s46, 0, 0x14000
	v_add_u32_e32 v124, s44, v248
	v_add_u32_e32 v144, s46, v248
	ds_read_b128 v[88:91], v124
	ds_read_b128 v[100:103], v124 offset:1024
	ds_read_b128 v[112:115], v124 offset:2048
	ds_read_b128 v[124:127], v124 offset:3072
	ds_read_b128 v[128:131], v144
	ds_read_b128 v[132:135], v144 offset:1024
	ds_read_b128 v[136:139], v144 offset:2048
	ds_read_b128 v[144:147], v144 offset:3072
	v_lshl_add_u64 v[192:193], s[34:35], 0, v[224:225]
	s_add_i32 m0, s95, 0xc000
	ds_read_b128 v[152:155], v249
	ds_read_b128 v[156:159], v249 offset:1024
	ds_read_b128 v[168:171], v249 offset:2048
	ds_read_b128 v[172:175], v249 offset:3072
	ds_read_b128 v[176:179], v249 offset:4096
	ds_read_b128 v[180:183], v249 offset:5120
	ds_read_b128 v[184:187], v249 offset:6144
	ds_read_b128 v[188:191], v249 offset:7168
	global_load_lds_dwordx4 v[192:193], off
	v_lshl_add_u64 v[192:193], s[34:35], 0, v[226:227]
	s_add_i32 m0, s95, 0xe000
	s_nop 0
	global_load_lds_dwordx4 v[192:193], off
	s_waitcnt vmcnt(8)
	s_waitcnt lgkmcnt(0)
	s_barrier
	s_setprio 1
	s_waitcnt lgkmcnt(0)
	v_mfma_f32_16x16x32_bf16 v[164:167], v[88:91], v[152:155], 0
	v_mfma_f32_16x16x32_bf16 v[160:163], v[112:115], v[152:155], 0
	v_mfma_f32_16x16x32_bf16 v[120:123], v[88:91], v[168:171], 0
	v_mfma_f32_16x16x32_bf16 v[116:119], v[112:115], v[168:171], 0
	v_mfma_f32_16x16x32_bf16 v[96:99], v[88:91], v[176:179], 0
	v_mfma_f32_16x16x32_bf16 v[92:95], v[112:115], v[176:179], 0
	v_mfma_f32_16x16x32_bf16 v[76:79], v[88:91], v[184:187], 0
	v_mfma_f32_16x16x32_bf16 v[72:75], v[112:115], v[184:187], 0
	v_mfma_f32_16x16x32_bf16 v[164:167], v[100:103], v[156:159], v[164:167]
	v_mfma_f32_16x16x32_bf16 v[160:163], v[124:127], v[156:159], v[160:163]
	v_mfma_f32_16x16x32_bf16 v[120:123], v[100:103], v[172:175], v[120:123]
	v_mfma_f32_16x16x32_bf16 v[116:119], v[124:127], v[172:175], v[116:119]
	v_mfma_f32_16x16x32_bf16 v[96:99], v[100:103], v[180:183], v[96:99]
	v_mfma_f32_16x16x32_bf16 v[92:95], v[124:127], v[180:183], v[92:95]
	v_mfma_f32_16x16x32_bf16 v[76:79], v[100:103], v[188:191], v[76:79]
	v_mfma_f32_16x16x32_bf16 v[72:75], v[124:127], v[188:191], v[72:75]
	s_setprio 0
	s_setprio 1
	v_mfma_f32_16x16x32_bf16 v[148:151], v[128:131], v[152:155], 0
	v_mfma_f32_16x16x32_bf16 v[140:143], v[136:139], v[152:155], 0
	v_mfma_f32_16x16x32_bf16 v[108:111], v[128:131], v[168:171], 0
	v_mfma_f32_16x16x32_bf16 v[104:107], v[136:139], v[168:171], 0
	v_mfma_f32_16x16x32_bf16 v[84:87], v[128:131], v[176:179], 0
	v_mfma_f32_16x16x32_bf16 v[80:83], v[136:139], v[176:179], 0
	v_mfma_f32_16x16x32_bf16 v[68:71], v[128:131], v[184:187], 0
	v_mfma_f32_16x16x32_bf16 v[64:67], v[136:139], v[184:187], 0
	v_mfma_f32_16x16x32_bf16 v[148:151], v[132:135], v[156:159], v[148:151]
	v_mfma_f32_16x16x32_bf16 v[140:143], v[144:147], v[156:159], v[140:143]
	v_mfma_f32_16x16x32_bf16 v[108:111], v[132:135], v[172:175], v[108:111]
	v_mfma_f32_16x16x32_bf16 v[104:107], v[144:147], v[172:175], v[104:107]
	v_mfma_f32_16x16x32_bf16 v[84:87], v[132:135], v[180:183], v[84:87]
	v_mfma_f32_16x16x32_bf16 v[80:83], v[144:147], v[180:183], v[80:83]
	v_mfma_f32_16x16x32_bf16 v[68:71], v[132:135], v[188:191], v[68:71]
	v_mfma_f32_16x16x32_bf16 v[64:67], v[144:147], v[188:191], v[64:67]
	s_setprio 0
	s_barrier
	s_add_i32 s44, s44, s94
	v_lshl_add_u64 v[192:193], s[40:41], 0, v[208:209]
	s_mov_b32 m0, s44
	ds_read_b128 v[152:155], v249 offset:16384
	ds_read_b128 v[156:159], v249 offset:17408
	ds_read_b128 v[168:171], v249 offset:18432
	ds_read_b128 v[172:175], v249 offset:19456
	ds_read_b128 v[176:179], v249 offset:20480
	ds_read_b128 v[180:183], v249 offset:21504
	ds_read_b128 v[184:187], v249 offset:22528
	ds_read_b128 v[188:191], v249 offset:23552
	global_load_lds_dwordx4 v[192:193], off
	s_add_i32 m0, s44, 0x2000
	s_add_u32 s44, s40, 0xb0000
	v_lshl_add_u64 v[194:195], s[40:41], 0, v[222:223]
	s_addc_u32 s45, s41, 0
	s_add_i32 s46, s46, s94
	global_load_lds_dwordx4 v[194:195], off
	v_lshl_add_u64 v[196:197], s[44:45], 0, v[208:209]
	s_mov_b32 m0, s46
	s_nop 0
	global_load_lds_dwordx4 v[196:197], off
	v_lshl_add_u64 v[196:197], s[44:45], 0, v[222:223]
	s_add_i32 m0, s46, 0x2000
	s_nop 0
	global_load_lds_dwordx4 v[196:197], off
	v_lshl_add_u64 v[196:197], s[42:43], 0, v[218:219]
	s_mov_b32 m0, s95
	s_nop 0
	global_load_lds_dwordx4 v[196:197], off
	v_lshl_add_u64 v[196:197], s[42:43], 0, v[220:221]
	s_mov_b32 m0, s18
	s_nop 0
	global_load_lds_dwordx4 v[196:197], off
	s_waitcnt vmcnt(8)
	s_waitcnt lgkmcnt(0)
	s_barrier
	s_setprio 1
	s_waitcnt lgkmcnt(0)
	v_mfma_f32_16x16x32_bf16 v[60:63], v[88:91], v[152:155], 0
	v_mfma_f32_16x16x32_bf16 v[56:59], v[112:115], v[152:155], 0
	v_mfma_f32_16x16x32_bf16 v[44:47], v[88:91], v[168:171], 0
	v_mfma_f32_16x16x32_bf16 v[40:43], v[112:115], v[168:171], 0
	v_mfma_f32_16x16x32_bf16 v[28:31], v[88:91], v[176:179], 0
	v_mfma_f32_16x16x32_bf16 v[24:27], v[112:115], v[176:179], 0
	v_mfma_f32_16x16x32_bf16 v[12:15], v[88:91], v[184:187], 0
	v_mfma_f32_16x16x32_bf16 v[8:11], v[112:115], v[184:187], 0
	v_mfma_f32_16x16x32_bf16 v[60:63], v[100:103], v[156:159], v[60:63]
	v_mfma_f32_16x16x32_bf16 v[56:59], v[124:127], v[156:159], v[56:59]
	v_mfma_f32_16x16x32_bf16 v[44:47], v[100:103], v[172:175], v[44:47]
	v_mfma_f32_16x16x32_bf16 v[40:43], v[124:127], v[172:175], v[40:43]
	v_mfma_f32_16x16x32_bf16 v[28:31], v[100:103], v[180:183], v[28:31]
	v_mfma_f32_16x16x32_bf16 v[24:27], v[124:127], v[180:183], v[24:27]
	v_mfma_f32_16x16x32_bf16 v[12:15], v[100:103], v[188:191], v[12:15]
	v_mfma_f32_16x16x32_bf16 v[8:11], v[124:127], v[188:191], v[8:11]
	s_setprio 0
	s_setprio 1
	v_mfma_f32_16x16x32_bf16 v[52:55], v[128:131], v[152:155], 0
	v_mfma_f32_16x16x32_bf16 v[48:51], v[136:139], v[152:155], 0
	v_mfma_f32_16x16x32_bf16 v[36:39], v[128:131], v[168:171], 0
	v_mfma_f32_16x16x32_bf16 v[32:35], v[136:139], v[168:171], 0
	v_mfma_f32_16x16x32_bf16 v[20:23], v[128:131], v[176:179], 0
	v_mfma_f32_16x16x32_bf16 v[16:19], v[136:139], v[176:179], 0
	v_mfma_f32_16x16x32_bf16 v[4:7], v[128:131], v[184:187], 0
	v_mfma_f32_16x16x32_bf16 v[0:3], v[136:139], v[184:187], 0
	v_mfma_f32_16x16x32_bf16 v[52:55], v[132:135], v[156:159], v[52:55]
	v_mfma_f32_16x16x32_bf16 v[48:51], v[144:147], v[156:159], v[48:51]
	v_mfma_f32_16x16x32_bf16 v[36:39], v[132:135], v[172:175], v[36:39]
	v_mfma_f32_16x16x32_bf16 v[32:35], v[144:147], v[172:175], v[32:35]
	v_mfma_f32_16x16x32_bf16 v[20:23], v[132:135], v[180:183], v[20:23]
	v_mfma_f32_16x16x32_bf16 v[16:19], v[144:147], v[180:183], v[16:19]
	v_mfma_f32_16x16x32_bf16 v[4:7], v[132:135], v[188:191], v[4:7]
	v_mfma_f32_16x16x32_bf16 v[0:3], v[144:147], v[188:191], v[0:3]
	s_setprio 0
	s_barrier
	s_branch .Ldown_mid

.Ldown_mid:
	s_add_i32 s44, 0, 0x18000
	s_add_i32 s45, 0, 0x1c000
	v_add_u32_e32 v124, s44, v248
	v_add_u32_e32 v144, s45, v248
	ds_read_b128 v[88:91], v124
	ds_read_b128 v[100:103], v124 offset:1024
	ds_read_b128 v[112:115], v124 offset:2048
	ds_read_b128 v[124:127], v124 offset:3072
	ds_read_b128 v[128:131], v144
	ds_read_b128 v[132:135], v144 offset:1024
	ds_read_b128 v[136:139], v144 offset:2048
	ds_read_b128 v[144:147], v144 offset:3072
	s_add_u32 s42, s42, 0x2000
	s_addc_u32 s43, s43, 0
	s_mov_b32 m0, s19
	v_lshl_add_u64 v[196:197], s[42:43], 0, v[218:219]
	ds_read_b128 v[152:155], v249 offset:32768
	ds_read_b128 v[156:159], v249 offset:33792
	ds_read_b128 v[168:171], v249 offset:34816
	ds_read_b128 v[172:175], v249 offset:35840
	ds_read_b128 v[176:179], v249 offset:36864
	ds_read_b128 v[180:183], v249 offset:37888
	ds_read_b128 v[184:187], v249 offset:38912
	ds_read_b128 v[188:191], v249 offset:39936
	global_load_lds_dwordx4 v[196:197], off
	v_lshl_add_u64 v[196:197], s[42:43], 0, v[220:221]
	s_mov_b32 m0, s66
	s_nop 0
	global_load_lds_dwordx4 v[196:197], off
	s_waitcnt vmcnt(8)
	s_waitcnt lgkmcnt(0)
	s_barrier
	s_setprio 1
	s_waitcnt lgkmcnt(0)
	v_mfma_f32_16x16x32_bf16 v[164:167], v[88:91], v[152:155], v[164:167]
	v_mfma_f32_16x16x32_bf16 v[160:163], v[112:115], v[152:155], v[160:163]
	v_mfma_f32_16x16x32_bf16 v[120:123], v[88:91], v[168:171], v[120:123]
	v_mfma_f32_16x16x32_bf16 v[116:119], v[112:115], v[168:171], v[116:119]
	v_mfma_f32_16x16x32_bf16 v[96:99], v[88:91], v[176:179], v[96:99]
	v_mfma_f32_16x16x32_bf16 v[92:95], v[112:115], v[176:179], v[92:95]
	v_mfma_f32_16x16x32_bf16 v[76:79], v[88:91], v[184:187], v[76:79]
	v_mfma_f32_16x16x32_bf16 v[72:75], v[112:115], v[184:187], v[72:75]
	v_mfma_f32_16x16x32_bf16 v[164:167], v[100:103], v[156:159], v[164:167]
	v_mfma_f32_16x16x32_bf16 v[160:163], v[124:127], v[156:159], v[160:163]
	v_mfma_f32_16x16x32_bf16 v[120:123], v[100:103], v[172:175], v[120:123]
	v_mfma_f32_16x16x32_bf16 v[116:119], v[124:127], v[172:175], v[116:119]
	v_mfma_f32_16x16x32_bf16 v[96:99], v[100:103], v[180:183], v[96:99]
	v_mfma_f32_16x16x32_bf16 v[92:95], v[124:127], v[180:183], v[92:95]
	v_mfma_f32_16x16x32_bf16 v[76:79], v[100:103], v[188:191], v[76:79]
	v_mfma_f32_16x16x32_bf16 v[72:75], v[124:127], v[188:191], v[72:75]
	s_setprio 0
	s_setprio 1
	v_mfma_f32_16x16x32_bf16 v[148:151], v[128:131], v[152:155], v[148:151]
	v_mfma_f32_16x16x32_bf16 v[140:143], v[136:139], v[152:155], v[140:143]
	v_mfma_f32_16x16x32_bf16 v[108:111], v[128:131], v[168:171], v[108:111]
	v_mfma_f32_16x16x32_bf16 v[104:107], v[136:139], v[168:171], v[104:107]
	v_mfma_f32_16x16x32_bf16 v[84:87], v[128:131], v[176:179], v[84:87]
	v_mfma_f32_16x16x32_bf16 v[80:83], v[136:139], v[176:179], v[80:83]
	v_mfma_f32_16x16x32_bf16 v[68:71], v[128:131], v[184:187], v[68:71]
	v_mfma_f32_16x16x32_bf16 v[64:67], v[136:139], v[184:187], v[64:67]
	v_mfma_f32_16x16x32_bf16 v[148:151], v[132:135], v[156:159], v[148:151]
	v_mfma_f32_16x16x32_bf16 v[140:143], v[144:147], v[156:159], v[140:143]
	v_mfma_f32_16x16x32_bf16 v[108:111], v[132:135], v[172:175], v[108:111]
	v_mfma_f32_16x16x32_bf16 v[104:107], v[144:147], v[172:175], v[104:107]
	v_mfma_f32_16x16x32_bf16 v[84:87], v[132:135], v[180:183], v[84:87]
	v_mfma_f32_16x16x32_bf16 v[80:83], v[144:147], v[180:183], v[80:83]
	v_mfma_f32_16x16x32_bf16 v[68:71], v[132:135], v[188:191], v[68:71]
	v_mfma_f32_16x16x32_bf16 v[64:67], v[144:147], v[188:191], v[64:67]
	s_setprio 0
	s_barrier
	s_add_i32 s42, s44, s94
	v_lshl_add_u64 v[192:193], v[192:193], 0, s[4:5]
	s_mov_b32 m0, s42
	ds_read_b128 v[152:155], v249 offset:49152
	ds_read_b128 v[156:159], v249 offset:50176
	ds_read_b128 v[168:171], v249 offset:51200
	ds_read_b128 v[172:175], v249 offset:52224
	ds_read_b128 v[176:179], v249 offset:53248
	ds_read_b128 v[180:183], v249 offset:54272
	ds_read_b128 v[184:187], v249 offset:55296
	ds_read_b128 v[188:191], v249 offset:56320
	global_load_lds_dwordx4 v[192:193], off
	s_add_i32 m0, s42, 0x2000
	s_add_u32 s40, s40, 0xb0080
	v_lshl_add_u64 v[192:193], v[194:195], 0, s[4:5]
	s_addc_u32 s41, s41, 0
	s_add_i32 s42, s45, s94
	global_load_lds_dwordx4 v[192:193], off
	v_lshl_add_u64 v[192:193], s[40:41], 0, v[208:209]
	s_mov_b32 m0, s42
	s_nop 0
	global_load_lds_dwordx4 v[192:193], off
	v_lshl_add_u64 v[192:193], s[40:41], 0, v[222:223]
	s_add_i32 m0, s42, 0x2000
	s_nop 0
	global_load_lds_dwordx4 v[192:193], off
	v_lshl_add_u64 v[192:193], s[38:39], 0, v[218:219]
	s_mov_b32 m0, s72
	s_nop 0
	global_load_lds_dwordx4 v[192:193], off
	v_lshl_add_u64 v[192:193], s[38:39], 0, v[220:221]
	s_mov_b32 m0, s73
	s_nop 0
	global_load_lds_dwordx4 v[192:193], off
	s_waitcnt vmcnt(8)
	s_waitcnt lgkmcnt(0)
	s_barrier
	s_setprio 1
	s_waitcnt lgkmcnt(0)
	v_mfma_f32_16x16x32_bf16 v[60:63], v[88:91], v[152:155], v[60:63]
	v_mfma_f32_16x16x32_bf16 v[56:59], v[112:115], v[152:155], v[56:59]
	v_mfma_f32_16x16x32_bf16 v[44:47], v[88:91], v[168:171], v[44:47]
	v_mfma_f32_16x16x32_bf16 v[40:43], v[112:115], v[168:171], v[40:43]
	v_mfma_f32_16x16x32_bf16 v[28:31], v[88:91], v[176:179], v[28:31]
	v_mfma_f32_16x16x32_bf16 v[24:27], v[112:115], v[176:179], v[24:27]
	v_mfma_f32_16x16x32_bf16 v[12:15], v[88:91], v[184:187], v[12:15]
	v_mfma_f32_16x16x32_bf16 v[8:11], v[112:115], v[184:187], v[8:11]
	v_mfma_f32_16x16x32_bf16 v[60:63], v[100:103], v[156:159], v[60:63]
	v_mfma_f32_16x16x32_bf16 v[56:59], v[124:127], v[156:159], v[56:59]
	v_mfma_f32_16x16x32_bf16 v[44:47], v[100:103], v[172:175], v[44:47]
	v_mfma_f32_16x16x32_bf16 v[40:43], v[124:127], v[172:175], v[40:43]
	v_mfma_f32_16x16x32_bf16 v[28:31], v[100:103], v[180:183], v[28:31]
	v_mfma_f32_16x16x32_bf16 v[24:27], v[124:127], v[180:183], v[24:27]
	v_mfma_f32_16x16x32_bf16 v[12:15], v[100:103], v[188:191], v[12:15]
	v_mfma_f32_16x16x32_bf16 v[8:11], v[124:127], v[188:191], v[8:11]
	s_setprio 0
	s_setprio 1
	v_mfma_f32_16x16x32_bf16 v[52:55], v[128:131], v[152:155], v[52:55]
	v_mfma_f32_16x16x32_bf16 v[48:51], v[136:139], v[152:155], v[48:51]
	v_mfma_f32_16x16x32_bf16 v[36:39], v[128:131], v[168:171], v[36:39]
	v_mfma_f32_16x16x32_bf16 v[32:35], v[136:139], v[168:171], v[32:35]
	v_mfma_f32_16x16x32_bf16 v[20:23], v[128:131], v[176:179], v[20:23]
	v_mfma_f32_16x16x32_bf16 v[16:19], v[136:139], v[176:179], v[16:19]
	v_mfma_f32_16x16x32_bf16 v[4:7], v[128:131], v[184:187], v[4:7]
	v_mfma_f32_16x16x32_bf16 v[0:3], v[136:139], v[184:187], v[0:3]
	v_mfma_f32_16x16x32_bf16 v[52:55], v[132:135], v[156:159], v[52:55]
	v_mfma_f32_16x16x32_bf16 v[48:51], v[144:147], v[156:159], v[48:51]
	v_mfma_f32_16x16x32_bf16 v[36:39], v[132:135], v[172:175], v[36:39]
	v_mfma_f32_16x16x32_bf16 v[32:35], v[144:147], v[172:175], v[32:35]
	v_mfma_f32_16x16x32_bf16 v[20:23], v[132:135], v[180:183], v[20:23]
	v_mfma_f32_16x16x32_bf16 v[16:19], v[144:147], v[180:183], v[16:19]
	v_mfma_f32_16x16x32_bf16 v[4:7], v[132:135], v[188:191], v[4:7]
	v_mfma_f32_16x16x32_bf16 v[0:3], v[144:147], v[188:191], v[0:3]
	s_setprio 0
	s_barrier
	s_add_i32 s27, s27, 2
	s_add_u32 s2, s2, 0x100
	s_addc_u32 s3, s3, 0
	s_add_u32 s34, s34, 0x10000
	s_addc_u32 s35, s35, 0
	s_cmp_gt_u32 s27, 41
	s_cbranch_scc0 .LBB0_654
	s_and_b64 vcc, exec, s[76:77]
	s_cbranch_vccz .LBB0_657
	s_barrier
